# attention PV block: lgkmcnt(0) after the first 8 V-fragment transposed LDS reads replaced by counted lgkmcnt(6) waits before each of the 4 MFMAs
# speedup vs baseline: 1.0065x; 1.0045x over previous
; __device__ __forceinline__ void finishSM(f32x16& p0, f32x16& p1, float alpha, float& l_reg, bf16x8& pa0, bf16x8& pa1, bf16x8& pa2, bf16x8& pa3) {
; #pragma unroll
;     for (int r = 0; r < 16; ++r) p1[r] = __builtin_amdgcn_exp2f(p1[r]);
;     float ps = 0;
; #pragma unroll
;     for (int r = 0; r < 16; ++r) ps += p0[r];
; #pragma unroll
;     for (int r = 0; r < 16; ++r) ps += p1[r];
;     { auto rr = __builtin_amdgcn_permlane32_swap(__float_as_uint(ps), __float_as_uint(ps), false, false);
;       ps = __uint_as_float(rr[0]) + __uint_as_float(rr[1]); }
;     l_reg = l_reg * alpha + ps;
;     ...
;     PK4(p0, 0, pa0); PK4(p0, 8, pa1); PK4(p1, 0, pa2); PK4(p1, 8, pa3);
;     ...
; }
; template <int KB, int DQK>
; __device__ __forceinline__ void qkt(f32x16& p0, f32x16& p1, const char* K_lds, int r32, int hi, const bf16x8* qr, const char* qrl) {
;     constexpr int SHMK = 64 * DQK * 2, NF = DQK / 16, NFR = NF > 8 ? 8 : NF;
;     p0 = f32x16{}; p1 = f32x16{};
;     const char* kb[4];
; #pragma unroll
;     for (int dd = 0; dd < 4; ++dd) kb[dd] = K_lds + KB * SHMK + kswz<DQK>(r32, (dd * 16 + hi * 8) * 2);
; #pragma unroll
;     for (int d0 = 0; d0 < NF; ++d0) { const char* a = kb[d0 & 3] + (d0 >> 2) * 128;
;         bf16x8 b0 = *reinterpret_cast<const bf16x8*>(a);
;         bf16x8 b1 = *reinterpret_cast<const bf16x8*>(a + 32 * DQK * 2);
;         bf16x8 q; if (d0 < NFR) q = qr[d0]; else q = *reinterpret_cast<const bf16x8*>(qrl + (d0 - NFR) * 1024);
;         p0 = __builtin_amdgcn_mfma_f32_32x32x16_bf16(b0, q, p0, 0, 0, 0);
;         p1 = __builtin_amdgcn_mfma_f32_32x32x16_bf16(b1, q, p1, 0, 0, 0); }
; }
.LBB0_526:
	ds_read_b128 v[66:69], v212 offset:57344
	ds_read_b128 v[70:73], v221 offset:12288
	ds_read_b128 v[186:189], v213 offset:57344
	ds_read_b128 v[226:229], v220 offset:12288
	v_add_f32_e32 v0, 0, v150
	v_add_f32_e32 v0, v163, v0
	s_waitcnt lgkmcnt(3)
	v_mfma_f32_32x32x16_bf16 v[82:97], v[66:69], v[126:129], 0
	v_add_f32_e32 v0, v151, v0
	v_add_f32_e32 v0, v161, v0
	v_add_f32_e32 v0, v152, v0
	v_add_f32_e32 v0, v160, v0
	v_add_f32_e32 v0, v153, v0
	v_add_f32_e32 v0, v159, v0
	v_add_f32_e32 v0, v154, v0
	s_waitcnt lgkmcnt(2)
	v_mfma_f32_32x32x16_bf16 v[66:81], v[70:73], v[126:129], 0
	v_add_f32_e32 v0, v158, v0
	v_add_f32_e32 v0, v155, v0
	v_add_f32_e32 v0, v157, v0
	v_exp_f32_e32 v138, v138
	v_add_f32_e32 v0, v148, v0
	v_exp_f32_e32 v139, v139
	v_add_f32_e32 v0, v156, v0
	s_waitcnt lgkmcnt(1)
	v_mfma_f32_32x32x16_bf16 v[82:97], v[186:189], v[122:125], v[82:97]
	v_exp_f32_e32 v142, v142
	v_add_f32_e32 v0, v147, v0
	v_exp_f32_e32 v143, v143
	v_add_f32_e32 v0, v149, v0
	v_exp_f32_e32 v130, v130
	v_add_f32_e32 v0, v138, v0
	v_exp_f32_e32 v131, v131
	s_waitcnt lgkmcnt(0)
	v_mfma_f32_32x32x16_bf16 v[66:81], v[226:229], v[122:125], v[66:81]
	ds_read_b128 v[186:189], v211 offset:57344
	ds_read_b128 v[226:229], v219 offset:12288
	v_add_f32_e32 v0, v139, v0
	v_exp_f32_e32 v136, v136
	v_add_f32_e32 v0, v142, v0
	v_exp_f32_e32 v137, v137
	v_add_f32_e32 v0, v143, v0
	v_exp_f32_e32 v140, v140
	s_waitcnt lgkmcnt(1)
	v_mfma_f32_32x32x16_bf16 v[82:97], v[186:189], v[118:121], v[82:97]
	v_add_f32_e32 v0, v130, v0
	v_exp_f32_e32 v141, v141
	v_add_f32_e32 v0, v131, v0
	v_exp_f32_e32 v144, v144
	v_add_f32_e32 v0, v136, v0
	v_exp_f32_e32 v145, v145
	v_add_f32_e32 v0, v137, v0
	s_waitcnt lgkmcnt(0)
	v_mfma_f32_32x32x16_bf16 v[66:81], v[226:229], v[118:121], v[66:81]
	ds_read_b128 v[186:189], v210 offset:57344
	ds_read_b128 v[226:229], v218 offset:12288
	v_exp_f32_e32 v132, v132
	v_add_f32_e32 v0, v140, v0
	v_exp_f32_e32 v133, v133
	v_add_f32_e32 v0, v141, v0
	v_exp_f32_e32 v134, v134
	v_add_f32_e32 v0, v144, v0
	s_waitcnt lgkmcnt(1)
	v_mfma_f32_32x32x16_bf16 v[82:97], v[186:189], v[114:117], v[82:97]
	v_exp_f32_e32 v135, v135
	v_add_f32_e32 v0, v145, v0
	v_add_f32_e32 v0, v132, v0
	v_add_f32_e32 v0, v133, v0
	v_add_f32_e32 v0, v134, v0
	v_add_f32_e32 v0, v135, v0
	v_mov_b32_e32 v225, v0
	s_waitcnt lgkmcnt(0)
	v_mfma_f32_32x32x16_bf16 v[66:81], v[226:229], v[114:117], v[66:81]
	ds_read_b128 v[186:189], v212 offset:57472
	ds_read_b128 v[226:229], v221 offset:12416
	v_permlane32_swap_b32_e32 v0, v225
	s_waitcnt lgkmcnt(1)
	v_mfma_f32_32x32x16_bf16 v[82:97], v[186:189], v[102:105], v[82:97]
	s_waitcnt lgkmcnt(0)
	v_mfma_f32_32x32x16_bf16 v[66:81], v[226:229], v[102:105], v[66:81]
	ds_read_b128 v[186:189], v213 offset:57472
	ds_read_b128 v[226:229], v220 offset:12416
	s_waitcnt lgkmcnt(1)
	v_mfma_f32_32x32x16_bf16 v[82:97], v[186:189], v[98:101], v[82:97]
	s_waitcnt lgkmcnt(0)
	v_mfma_f32_32x32x16_bf16 v[66:81], v[226:229], v[98:101], v[66:81]
	ds_read_b128 v[186:189], v211 offset:57472
	ds_read_b128 v[226:229], v219 offset:12416
	s_waitcnt lgkmcnt(1)
	v_mfma_f32_32x32x16_bf16 v[82:97], v[186:189], v[110:113], v[82:97]
	s_waitcnt lgkmcnt(0)
	v_mfma_f32_32x32x16_bf16 v[66:81], v[226:229], v[110:113], v[66:81]
	ds_read_b128 v[186:189], v210 offset:57472
	ds_read_b128 v[226:229], v218 offset:12416
	s_waitcnt lgkmcnt(1)
	v_mfma_f32_32x32x16_bf16 v[82:97], v[186:189], v[106:109], v[82:97]
	s_waitcnt lgkmcnt(0)
	v_mfma_f32_32x32x16_bf16 v[66:81], v[226:229], v[106:109], v[66:81]
	ds_read_b128 v[186:189], v212 offset:57600
	ds_read_b128 v[226:229], v221 offset:12544
	ds_read_b128 v[230:233], v209
	s_waitcnt lgkmcnt(0)
	v_mfma_f32_32x32x16_bf16 v[82:97], v[186:189], v[230:233], v[82:97]
	v_mfma_f32_32x32x16_bf16 v[66:81], v[226:229], v[230:233], v[66:81]
	ds_read_b128 v[186:189], v213 offset:57600
	ds_read_b128 v[226:229], v220 offset:12544
	ds_read_b128 v[230:233], v209 offset:1024
	s_waitcnt lgkmcnt(0)
	v_mfma_f32_32x32x16_bf16 v[82:97], v[186:189], v[230:233], v[82:97]
	v_mfma_f32_32x32x16_bf16 v[66:81], v[226:229], v[230:233], v[66:81]
	ds_read_b128 v[186:189], v211 offset:57600
	ds_read_b128 v[226:229], v219 offset:12544
	ds_read_b128 v[230:233], v209 offset:2048
	s_waitcnt lgkmcnt(0)
	v_mfma_f32_32x32x16_bf16 v[82:97], v[186:189], v[230:233], v[82:97]
	v_mfma_f32_32x32x16_bf16 v[66:81], v[226:229], v[230:233], v[66:81]
	ds_read_b128 v[186:189], v210 offset:57600
	ds_read_b128 v[226:229], v218 offset:12544
	ds_read_b128 v[230:233], v209 offset:3072
	v_cvt_pk_bf16_f32 v150, v150, v163
	v_cvt_pk_bf16_f32 v151, v151, v161
	v_cvt_pk_bf16_f32 v152, v152, v160
	v_cvt_pk_bf16_f32 v153, v153, v159
	v_cvt_pk_bf16_f32 v154, v154, v158
	v_cvt_pk_bf16_f32 v155, v155, v157
	s_waitcnt lgkmcnt(0)
; __device__ __forceinline__ void finishSM(f32x16& p0, f32x16& p1, float alpha, float& l_reg, bf16x8& pa0, bf16x8& pa1, bf16x8& pa2, bf16x8& pa3) {
;     ...
;     PK4(p0, 0, pa0); PK4(p0, 8, pa1); PK4(p1, 0, pa2); PK4(p1, 8, pa3);
; template <int VB>
; __device__ __forceinline__ void pv_tile(f32x16* o, int vb0, bf16x8 pa0, bf16x8 pa1, bf16x8 pa2, bf16x8 pa3) {
;     ...
;     PV_D0(0); PV_D0(1); PV_D0(2); PV_D0(3);
	v_mfma_f32_32x32x16_bf16 v[82:97], v[186:189], v[230:233], v[82:97]
	v_cvt_pk_bf16_f32 v156, v148, v156
	v_cvt_pk_bf16_f32 v157, v147, v149
	v_cvt_pk_bf16_f32 v158, v138, v139
	v_cvt_pk_bf16_f32 v159, v142, v143
	v_cvt_pk_bf16_f32 v160, v130, v131
	v_cvt_pk_bf16_f32 v161, v136, v137
	v_permlane32_swap_b32_e32 v150, v152
	v_mfma_f32_32x32x16_bf16 v[66:81], v[226:229], v[230:233], v[66:81]
	v_cvt_pk_bf16_f32 v226, v140, v141
	v_cvt_pk_bf16_f32 v227, v144, v145
	v_cvt_pk_bf16_f32 v228, v132, v133
	v_cvt_pk_bf16_f32 v229, v134, v135
	v_permlane32_swap_b32_e32 v151, v153
	v_permlane32_swap_b32_e32 v154, v156
	v_permlane32_swap_b32_e32 v155, v157
	v_permlane32_swap_b32_e32 v158, v160
	v_permlane32_swap_b32_e32 v159, v161
	v_permlane32_swap_b32_e32 v226, v228
	v_permlane32_swap_b32_e32 v227, v229
	v_lshl_add_u64 v[190:191], s[14:15], 0, v[182:183]
	v_add_co_u32_e32 v130, vcc, s19, v190
	v_lshl_add_u64 v[186:187], s[14:15], 0, v[184:185]
	s_nop 0
	v_addc_co_u32_e32 v131, vcc, 0, v191, vcc
	v_add_co_u32_e32 v134, vcc, s31, v190
	v_lshl_add_u64 v[188:189], s[14:15], 0, v[180:181]
	s_nop 0
	v_addc_co_u32_e32 v135, vcc, 0, v191, vcc
	v_add_co_u32_e32 v138, vcc, s19, v186
	global_load_dwordx4 v[130:133], v[130:131], off offset:1024
	s_nop 0
	global_load_dwordx4 v[134:137], v[134:135], off offset:1024
	v_addc_co_u32_e32 v139, vcc, 0, v187, vcc
	v_add_co_u32_e32 v142, vcc, s31, v186
	s_nop 1
	v_addc_co_u32_e32 v143, vcc, 0, v187, vcc
	v_add_co_u32_e32 v146, vcc, s20, v188
	global_load_dwordx4 v[138:141], v[138:139], off
	s_nop 0
	global_load_dwordx4 v[142:145], v[142:143], off
	v_addc_co_u32_e32 v147, vcc, 0, v189, vcc
	global_load_dwordx4 v[146:149], v[146:147], off offset:1280
	ds_read_b64_tr_b16 v[230:231], v195 offset:0
	ds_read_b64_tr_b16 v[232:233], v195 offset:0x800
	ds_read_b64_tr_b16 v[234:235], v195 offset:0x1000
	ds_read_b64_tr_b16 v[236:237], v195 offset:0x1800
	ds_read_b64_tr_b16 v[238:239], v195 offset:0x2000
	ds_read_b64_tr_b16 v[240:241], v195 offset:0x2800
	ds_read_b64_tr_b16 v[242:243], v195 offset:0x3000
	ds_read_b64_tr_b16 v[244:245], v195 offset:0x3800
	s_waitcnt lgkmcnt(6)
	s_nop 0
	v_mfma_f32_32x32x16_bf16 v[50:65], v[150:153], v[230:233], v[50:65]
	ds_read_b64_tr_b16 v[230:231], v195 offset:0x200
	ds_read_b64_tr_b16 v[232:233], v195 offset:0xa00
	s_waitcnt lgkmcnt(6)
	v_mfma_f32_32x32x16_bf16 v[50:65], v[154:157], v[234:237], v[50:65]
	ds_read_b64_tr_b16 v[234:235], v195 offset:0x1200
	ds_read_b64_tr_b16 v[236:237], v195 offset:0x1a00
	s_waitcnt lgkmcnt(6)
	v_mfma_f32_32x32x16_bf16 v[50:65], v[158:161], v[238:241], v[50:65]
	ds_read_b64_tr_b16 v[238:239], v195 offset:0x2200
	ds_read_b64_tr_b16 v[240:241], v195 offset:0x2a00
	s_waitcnt lgkmcnt(6)
	v_mfma_f32_32x32x16_bf16 v[50:65], v[226:229], v[242:245], v[50:65]
	ds_read_b64_tr_b16 v[242:243], v195 offset:0x3200
	ds_read_b64_tr_b16 v[244:245], v195 offset:0x3a00
	s_waitcnt lgkmcnt(0)
	v_mfma_f32_32x32x16_bf16 v[34:49], v[150:153], v[230:233], v[34:49]
	ds_read_b64_tr_b16 v[230:231], v195 offset:0x400
	ds_read_b64_tr_b16 v[232:233], v195 offset:0xc00
	v_mfma_f32_32x32x16_bf16 v[34:49], v[154:157], v[234:237], v[34:49]
	ds_read_b64_tr_b16 v[234:235], v195 offset:0x1400
	ds_read_b64_tr_b16 v[236:237], v195 offset:0x1c00
	v_mfma_f32_32x32x16_bf16 v[34:49], v[158:161], v[238:241], v[34:49]
	ds_read_b64_tr_b16 v[238:239], v195 offset:0x2400
	ds_read_b64_tr_b16 v[240:241], v195 offset:0x2c00
	v_mfma_f32_32x32x16_bf16 v[34:49], v[226:229], v[242:245], v[34:49]
	ds_read_b64_tr_b16 v[242:243], v195 offset:0x3400
	ds_read_b64_tr_b16 v[244:245], v195 offset:0x3c00
	s_waitcnt lgkmcnt(0)
	v_mfma_f32_32x32x16_bf16 v[18:33], v[150:153], v[230:233], v[18:33]
	ds_read_b64_tr_b16 v[230:231], v195 offset:0x600
	ds_read_b64_tr_b16 v[232:233], v195 offset:0xe00
	v_mfma_f32_32x32x16_bf16 v[18:33], v[154:157], v[234:237], v[18:33]
	ds_read_b64_tr_b16 v[234:235], v195 offset:0x1600
	ds_read_b64_tr_b16 v[236:237], v195 offset:0x1e00
	v_mfma_f32_32x32x16_bf16 v[18:33], v[158:161], v[238:241], v[18:33]
	ds_read_b64_tr_b16 v[238:239], v195 offset:0x2600
	ds_read_b64_tr_b16 v[240:241], v195 offset:0x2e00
	v_mfma_f32_32x32x16_bf16 v[18:33], v[226:229], v[242:245], v[18:33]
	ds_read_b64_tr_b16 v[242:243], v195 offset:0x3600
	ds_read_b64_tr_b16 v[244:245], v195 offset:0x3e00
	s_waitcnt lgkmcnt(0)
	v_mfma_f32_32x32x16_bf16 v[2:17], v[150:153], v[230:233], v[2:17]
	s_sub_i32 s4, s18, 64
	s_cmp_le_i32 s4, s2
	v_mfma_f32_32x32x16_bf16 v[2:17], v[154:157], v[234:237], v[2:17]
	v_mfma_f32_32x32x16_bf16 v[2:17], v[158:161], v[238:241], v[2:17]
	v_mfma_f32_32x32x16_bf16 v[2:17], v[226:229], v[242:245], v[2:17]
	s_cbranch_scc1 .LBB0_528
; __device__ __forceinline__ void mask_tile(f32x16& p0, f32x16& p1, int dq) {
;     const float NEG = -__builtin_inff();
; #pragma unroll
;     for (int r = 0; r < 16; ++r) {
;         const int c = (r & 3) + 8 * (r >> 2);
;         if (dq - c < 0) p0[r] = NEG;
;         if (dq - c - 32 < 0) p1[r] = NEG;
;     }
; }
	v_add_u32_e32 v150, 64, v224
	v_cmp_gt_i32_e64 s[96:97], 26, v150
	v_cmp_gt_i32_e32 vcc, 27, v150
	v_cmp_gt_i32_e64 s[94:95], 25, v150
	v_cmp_gt_i32_e64 s[92:93], 24, v150
	v_cndmask_b32_e32 v97, v97, v203, vcc
	s_and_b64 vcc, vcc, s[96:97]
	v_cndmask_b32_e32 v96, v96, v203, vcc
	s_and_b64 vcc, vcc, s[94:95]
	v_cmp_gt_i32_e64 s[90:91], 19, v150
	v_cndmask_b32_e32 v95, v95, v203, vcc
	s_and_b64 vcc, vcc, s[92:93]
	v_cmp_gt_i32_e64 s[88:89], 18, v150
	v_cndmask_b32_e32 v94, v94, v203, vcc
	s_and_b64 vcc, vcc, s[90:91]
	v_cmp_gt_i32_e64 s[86:87], 17, v150
	v_cndmask_b32_e32 v93, v93, v203, vcc
	s_and_b64 vcc, vcc, s[88:89]
	v_cmp_gt_i32_e64 s[84:85], 16, v150
	v_cndmask_b32_e32 v92, v92, v203, vcc
	s_and_b64 vcc, vcc, s[86:87]
	v_cmp_gt_i32_e64 s[82:83], 11, v150
	v_cndmask_b32_e32 v91, v91, v203, vcc
	s_and_b64 vcc, vcc, s[84:85]
	v_cmp_gt_i32_e64 s[80:81], 10, v150
	v_cndmask_b32_e32 v90, v90, v203, vcc
	s_and_b64 vcc, vcc, s[82:83]
	v_cmp_gt_i32_e64 s[78:79], 9, v150
	v_cndmask_b32_e32 v89, v89, v203, vcc
	s_and_b64 vcc, vcc, s[80:81]
	v_cmp_gt_i32_e64 s[76:77], 8, v150
	v_cndmask_b32_e32 v88, v88, v203, vcc
	s_and_b64 vcc, vcc, s[78:79]
	v_cmp_gt_i32_e64 s[74:75], 3, v150
	v_cndmask_b32_e32 v87, v87, v203, vcc
	s_and_b64 vcc, vcc, s[76:77]
	v_cmp_gt_i32_e64 s[8:9], 2, v150
	v_cndmask_b32_e32 v86, v86, v203, vcc
	s_and_b64 vcc, vcc, s[74:75]
	v_cmp_gt_i32_e64 s[6:7], 1, v150
	v_cndmask_b32_e32 v85, v85, v203, vcc
	s_and_b64 vcc, vcc, s[8:9]
	v_cmp_gt_i32_e64 s[4:5], 0, v150
	v_cndmask_b32_e32 v84, v84, v203, vcc
	s_and_b64 vcc, vcc, s[6:7]
	v_cndmask_b32_e32 v83, v83, v203, vcc
	s_and_b64 vcc, vcc, s[4:5]
	v_cmp_gt_i32_e64 s[70:71], 58, v150
	v_cndmask_b32_e32 v82, v82, v203, vcc
	v_cmp_gt_i32_e32 vcc, 59, v150
	v_cmp_gt_i32_e64 s[68:69], 57, v150
	v_cmp_gt_i32_e64 s[66:67], 56, v150
	v_cndmask_b32_e32 v81, v81, v203, vcc
	s_and_b64 vcc, vcc, s[70:71]
	v_cndmask_b32_e32 v80, v80, v203, vcc
	s_and_b64 vcc, vcc, s[68:69]
	v_cmp_gt_i32_e64 s[64:65], 51, v150
	v_cndmask_b32_e32 v79, v79, v203, vcc
	s_and_b64 vcc, vcc, s[66:67]
	v_cmp_gt_i32_e64 s[62:63], 50, v150
	v_cndmask_b32_e32 v78, v78, v203, vcc
	s_and_b64 vcc, vcc, s[64:65]
	v_cmp_gt_i32_e64 s[60:61], 49, v150
	v_cndmask_b32_e32 v77, v77, v203, vcc
	s_and_b64 vcc, vcc, s[62:63]
	v_cmp_gt_i32_e64 s[58:59], 48, v150
	v_cndmask_b32_e32 v76, v76, v203, vcc
	s_and_b64 vcc, vcc, s[60:61]
	v_cmp_gt_i32_e64 s[56:57], 43, v150
	v_cndmask_b32_e32 v75, v75, v203, vcc
	s_and_b64 vcc, vcc, s[58:59]
	v_cmp_gt_i32_e64 s[54:55], 42, v150
	v_cndmask_b32_e32 v74, v74, v203, vcc
	s_and_b64 vcc, vcc, s[56:57]
	v_cmp_gt_i32_e64 s[52:53], 41, v150
	v_cndmask_b32_e32 v73, v73, v203, vcc
	s_and_b64 vcc, vcc, s[54:55]
	v_cmp_gt_i32_e64 s[50:51], 40, v150
	v_cndmask_b32_e32 v72, v72, v203, vcc
	s_and_b64 vcc, vcc, s[52:53]
	v_cmp_gt_i32_e64 s[48:49], 35, v150
	v_cndmask_b32_e32 v71, v71, v203, vcc
	s_and_b64 vcc, vcc, s[50:51]
	v_cmp_gt_i32_e64 s[46:47], 34, v150
	v_cndmask_b32_e32 v70, v70, v203, vcc
	s_and_b64 vcc, vcc, s[48:49]
	v_cmp_gt_i32_e64 s[44:45], 33, v150
	v_cndmask_b32_e32 v69, v69, v203, vcc
	s_and_b64 vcc, vcc, s[46:47]
	v_cmp_gt_i32_e64 s[10:11], 32, v150
	v_cndmask_b32_e32 v68, v68, v203, vcc
	s_and_b64 vcc, vcc, s[44:45]
	v_cndmask_b32_e32 v67, v67, v203, vcc
	s_and_b64 vcc, vcc, s[10:11]
	v_cndmask_b32_e32 v66, v66, v203, vcc

; __device__ __forceinline__ void mask_tile(f32x16& p0, f32x16& p1, int dq) {
;     const float NEG = -__builtin_inff();
; #pragma unroll
;     for (int r = 0; r < 16; ++r) {
;         const int c = (r & 3) + 8 * (r >> 2);
;         if (dq - c < 0) p0[r] = NEG;
;         if (dq - c - 32 < 0) p1[r] = NEG;
;     }
; }
; template <int VB>
; __device__ __forceinline__ void pv_tile(f32x16* o, int vb0, bf16x8 pa0, bf16x8 pa1, bf16x8 pa2, bf16x8 pa3) {
;     ...
;     PV_D0(0); PV_D0(1); PV_D0(2); PV_D0(3);
.LBB0_534:
	ds_read_b64_tr_b16 v[186:187], v195 offset:0x4000
	ds_read_b64_tr_b16 v[188:189], v195 offset:0x4800
	ds_read_b64_tr_b16 v[230:231], v195 offset:0x5000
	ds_read_b64_tr_b16 v[232:233], v195 offset:0x5800
	ds_read_b64_tr_b16 v[234:235], v195 offset:0x6000
	ds_read_b64_tr_b16 v[236:237], v195 offset:0x6800
	ds_read_b64_tr_b16 v[238:239], v195 offset:0x7000
	ds_read_b64_tr_b16 v[240:241], v195 offset:0x7800
	s_waitcnt lgkmcnt(6)
	s_nop 0
	v_mfma_f32_32x32x16_bf16 v[50:65], v[150:153], v[186:189], v[50:65]
	ds_read_b64_tr_b16 v[186:187], v195 offset:0x4200
	ds_read_b64_tr_b16 v[188:189], v195 offset:0x4a00
	s_waitcnt lgkmcnt(6)
	v_mfma_f32_32x32x16_bf16 v[50:65], v[154:157], v[230:233], v[50:65]
	ds_read_b64_tr_b16 v[230:231], v195 offset:0x5200
	ds_read_b64_tr_b16 v[232:233], v195 offset:0x5a00
	s_waitcnt lgkmcnt(6)
	v_mfma_f32_32x32x16_bf16 v[50:65], v[158:161], v[234:237], v[50:65]
	ds_read_b64_tr_b16 v[234:235], v195 offset:0x6200
	ds_read_b64_tr_b16 v[236:237], v195 offset:0x6a00
	s_waitcnt lgkmcnt(6)
	v_mfma_f32_32x32x16_bf16 v[50:65], v[162:165], v[238:241], v[50:65]
	ds_read_b64_tr_b16 v[238:239], v195 offset:0x7200
	ds_read_b64_tr_b16 v[240:241], v195 offset:0x7a00
	s_waitcnt lgkmcnt(0)
	v_mfma_f32_32x32x16_bf16 v[34:49], v[150:153], v[186:189], v[34:49]
	ds_read_b64_tr_b16 v[186:187], v195 offset:0x4400
	ds_read_b64_tr_b16 v[188:189], v195 offset:0x4c00
	v_mfma_f32_32x32x16_bf16 v[34:49], v[154:157], v[230:233], v[34:49]
	ds_read_b64_tr_b16 v[230:231], v195 offset:0x5400
	ds_read_b64_tr_b16 v[232:233], v195 offset:0x5c00
	v_mfma_f32_32x32x16_bf16 v[34:49], v[158:161], v[234:237], v[34:49]
	ds_read_b64_tr_b16 v[234:235], v195 offset:0x6400
	ds_read_b64_tr_b16 v[236:237], v195 offset:0x6c00
	v_mfma_f32_32x32x16_bf16 v[34:49], v[162:165], v[238:241], v[34:49]
	ds_read_b64_tr_b16 v[238:239], v195 offset:0x7400
	ds_read_b64_tr_b16 v[240:241], v195 offset:0x7c00
	s_waitcnt lgkmcnt(0)
	v_mfma_f32_32x32x16_bf16 v[18:33], v[150:153], v[186:189], v[18:33]
	ds_read_b64_tr_b16 v[186:187], v195 offset:0x4600
	ds_read_b64_tr_b16 v[188:189], v195 offset:0x4e00
	v_mfma_f32_32x32x16_bf16 v[18:33], v[154:157], v[230:233], v[18:33]
	ds_read_b64_tr_b16 v[230:231], v195 offset:0x5600
	ds_read_b64_tr_b16 v[232:233], v195 offset:0x5e00
	v_mfma_f32_32x32x16_bf16 v[18:33], v[158:161], v[234:237], v[18:33]
	ds_read_b64_tr_b16 v[234:235], v195 offset:0x6600
	ds_read_b64_tr_b16 v[236:237], v195 offset:0x6e00
	v_mfma_f32_32x32x16_bf16 v[18:33], v[162:165], v[238:241], v[18:33]
	ds_read_b64_tr_b16 v[238:239], v195 offset:0x7600
	ds_read_b64_tr_b16 v[240:241], v195 offset:0x7e00
	s_waitcnt lgkmcnt(0)
	v_mfma_f32_32x32x16_bf16 v[2:17], v[150:153], v[186:189], v[2:17]
	s_cmp_le_i32 s18, s2
	v_mfma_f32_32x32x16_bf16 v[2:17], v[154:157], v[230:233], v[2:17]
	v_mfma_f32_32x32x16_bf16 v[2:17], v[158:161], v[234:237], v[2:17]
	v_mfma_f32_32x32x16_bf16 v[2:17], v[162:165], v[238:241], v[2:17]
	s_cbranch_scc1 .LBB0_536
	v_cmp_gt_i32_e64 s[94:95], 26, v224
	v_cmp_gt_i32_e64 s[96:97], 27, v224
	v_cmp_gt_i32_e64 s[92:93], 25, v224
	s_and_b64 s[94:95], s[96:97], s[94:95]
	v_cmp_gt_i32_e64 s[90:91], 24, v224
	s_and_b64 s[92:93], s[94:95], s[92:93]
	v_cmp_gt_i32_e64 s[88:89], 19, v224
	s_and_b64 s[90:91], s[92:93], s[90:91]
	v_cmp_gt_i32_e64 s[86:87], 18, v224
	s_and_b64 s[88:89], s[90:91], s[88:89]
	v_cmp_gt_i32_e64 s[84:85], 17, v224
	s_and_b64 s[86:87], s[88:89], s[86:87]
	v_cmp_gt_i32_e64 s[82:83], 16, v224
	s_and_b64 s[84:85], s[86:87], s[84:85]
	v_cmp_gt_i32_e64 s[80:81], 11, v224
	s_and_b64 s[82:83], s[84:85], s[82:83]
	v_cmp_gt_i32_e64 s[78:79], 10, v224
	s_and_b64 s[80:81], s[82:83], s[80:81]
	v_cmp_gt_i32_e64 s[76:77], 9, v224
	s_and_b64 s[78:79], s[80:81], s[78:79]
	v_cmp_gt_i32_e64 s[74:75], 8, v224
	s_and_b64 s[76:77], s[78:79], s[76:77]
	v_cmp_gt_i32_e64 s[10:11], 3, v224
	s_and_b64 s[74:75], s[76:77], s[74:75]
	v_cmp_gt_i32_e64 s[8:9], 2, v224
	s_and_b64 s[10:11], s[74:75], s[10:11]
	v_cmp_gt_i32_e64 s[6:7], 1, v224
	s_and_b64 s[8:9], s[10:11], s[8:9]
	v_cmp_gt_i32_e64 s[4:5], 0, v224
	s_and_b64 s[6:7], s[8:9], s[6:7]
	s_and_b64 s[4:5], s[6:7], s[4:5]
	v_cmp_gt_i32_e64 s[70:71], 58, v224
	v_cndmask_b32_e64 v82, v82, v203, s[4:5]
	v_cmp_gt_i32_e64 s[4:5], 59, v224
	v_cmp_gt_i32_e64 s[68:69], 57, v224
	v_cmp_gt_i32_e64 s[66:67], 56, v224
	v_cndmask_b32_e64 v81, v81, v203, s[4:5]
	s_and_b64 s[4:5], s[4:5], s[70:71]
	v_cndmask_b32_e64 v80, v80, v203, s[4:5]
	s_and_b64 s[4:5], s[4:5], s[68:69]
	v_cmp_gt_i32_e64 s[64:65], 51, v224
	v_cndmask_b32_e64 v79, v79, v203, s[4:5]
	s_and_b64 s[4:5], s[4:5], s[66:67]
	v_cmp_gt_i32_e64 s[62:63], 50, v224
	v_cndmask_b32_e64 v78, v78, v203, s[4:5]
	s_and_b64 s[4:5], s[4:5], s[64:65]
	v_cmp_gt_i32_e64 s[60:61], 49, v224
	v_cndmask_b32_e64 v77, v77, v203, s[4:5]
	s_and_b64 s[4:5], s[4:5], s[62:63]
	v_cmp_gt_i32_e64 s[58:59], 48, v224
	v_cndmask_b32_e64 v76, v76, v203, s[4:5]
	s_and_b64 s[4:5], s[4:5], s[60:61]
	v_cmp_gt_i32_e64 s[56:57], 43, v224
	v_cndmask_b32_e64 v75, v75, v203, s[4:5]
	s_and_b64 s[4:5], s[4:5], s[58:59]
	v_cmp_gt_i32_e64 s[54:55], 42, v224
	v_cndmask_b32_e64 v74, v74, v203, s[4:5]
	s_and_b64 s[4:5], s[4:5], s[56:57]
	v_cmp_gt_i32_e64 s[52:53], 41, v224
	v_cndmask_b32_e64 v73, v73, v203, s[4:5]
	s_and_b64 s[4:5], s[4:5], s[54:55]
	v_cmp_gt_i32_e64 s[50:51], 40, v224
	v_cndmask_b32_e64 v72, v72, v203, s[4:5]
	s_and_b64 s[4:5], s[4:5], s[52:53]
	v_cmp_gt_i32_e64 s[48:49], 35, v224
	v_cndmask_b32_e64 v71, v71, v203, s[4:5]
	s_and_b64 s[4:5], s[4:5], s[50:51]
	v_cmp_gt_i32_e64 s[46:47], 34, v224
	v_cndmask_b32_e64 v70, v70, v203, s[4:5]
	s_and_b64 s[4:5], s[4:5], s[48:49]
	v_cmp_gt_i32_e64 s[44:45], 33, v224
	v_cndmask_b32_e64 v69, v69, v203, s[4:5]
	s_and_b64 s[4:5], s[4:5], s[46:47]
	v_cmp_gt_i32_e32 vcc, 32, v224
	v_cndmask_b32_e64 v68, v68, v203, s[4:5]
	s_and_b64 s[4:5], s[4:5], s[44:45]
	s_and_b64 vcc, s[4:5], vcc
	v_cndmask_b32_e64 v97, v97, v203, s[96:97]
	v_cndmask_b32_e64 v96, v96, v203, s[94:95]
	v_cndmask_b32_e64 v95, v95, v203, s[92:93]
	v_cndmask_b32_e64 v94, v94, v203, s[90:91]
	v_cndmask_b32_e64 v93, v93, v203, s[88:89]
	v_cndmask_b32_e64 v92, v92, v203, s[86:87]
	v_cndmask_b32_e64 v91, v91, v203, s[84:85]
	v_cndmask_b32_e64 v90, v90, v203, s[82:83]
	v_cndmask_b32_e64 v89, v89, v203, s[80:81]
	v_cndmask_b32_e64 v88, v88, v203, s[78:79]
	v_cndmask_b32_e64 v87, v87, v203, s[76:77]
	v_cndmask_b32_e64 v86, v86, v203, s[74:75]
	v_cndmask_b32_e64 v85, v85, v203, s[10:11]
	v_cndmask_b32_e64 v84, v84, v203, s[8:9]
	v_cndmask_b32_e64 v83, v83, v203, s[6:7]
	v_cndmask_b32_e64 v67, v67, v203, s[4:5]
	v_cndmask_b32_e32 v66, v66, v203, vcc

; __device__ __forceinline__ void finishSM(f32x16& p0, f32x16& p1, float alpha, float& l_reg, bf16x8& pa0, bf16x8& pa1, bf16x8& pa2, bf16x8& pa3) {
; #pragma unroll
;     for (int r = 0; r < 16; ++r) p1[r] = __builtin_amdgcn_exp2f(p1[r]);
;     float ps = 0;
; #pragma unroll
;     for (int r = 0; r < 16; ++r) ps += p0[r];
; #pragma unroll
;     for (int r = 0; r < 16; ++r) ps += p1[r];
;     { auto rr = __builtin_amdgcn_permlane32_swap(__float_as_uint(ps), __float_as_uint(ps), false, false);
;       ps = __uint_as_float(rr[0]) + __uint_as_float(rr[1]); }
;     l_reg = l_reg * alpha + ps;
;     ...
;     PK4(p0, 0, pa0); PK4(p0, 8, pa1); PK4(p1, 0, pa2); PK4(p1, 8, pa3);
; template <int KB, int DQK>
; __device__ __forceinline__ void qkt(f32x16& p0, f32x16& p1, const char* K_lds, int r32, int hi, const bf16x8* qr, const char* qrl) {
;     constexpr int SHMK = 64 * DQK * 2, NF = DQK / 16, NFR = NF > 8 ? 8 : NF;
;     p0 = f32x16{}; p1 = f32x16{};
;     const char* kb[4];
; #pragma unroll
;     for (int dd = 0; dd < 4; ++dd) kb[dd] = K_lds + KB * SHMK + kswz<DQK>(r32, (dd * 16 + hi * 8) * 2);
; #pragma unroll
;     for (int d0 = 0; d0 < NF; ++d0) { const char* a = kb[d0 & 3] + (d0 >> 2) * 128;
;         bf16x8 b0 = *reinterpret_cast<const bf16x8*>(a);
;         bf16x8 b1 = *reinterpret_cast<const bf16x8*>(a + 32 * DQK * 2);
;         bf16x8 q; if (d0 < NFR) q = qr[d0]; else q = *reinterpret_cast<const bf16x8*>(qrl + (d0 - NFR) * 1024);
;         p0 = __builtin_amdgcn_mfma_f32_32x32x16_bf16(b0, q, p0, 0, 0, 0);
;         p1 = __builtin_amdgcn_mfma_f32_32x32x16_bf16(b1, q, p1, 0, 0, 0); }
.LBB0_544:
	ds_read_b128 v[66:69], v212 offset:57344
	ds_read_b128 v[70:73], v221 offset:12288
	s_waitcnt lgkmcnt(1)
	v_mfma_f32_32x32x16_bf16 v[82:97], v[66:69], v[126:129], 0
	s_waitcnt lgkmcnt(0)
	v_mfma_f32_32x32x16_bf16 v[66:81], v[70:73], v[126:129], 0
	ds_read_b128 v[126:129], v213 offset:57344
	ds_read_b128 v[180:183], v220 offset:12288
	s_waitcnt lgkmcnt(1)
	v_mfma_f32_32x32x16_bf16 v[82:97], v[126:129], v[122:125], v[82:97]
	s_waitcnt lgkmcnt(0)
	v_mfma_f32_32x32x16_bf16 v[66:81], v[180:183], v[122:125], v[66:81]
	ds_read_b128 v[122:125], v211 offset:57344
	ds_read_b128 v[126:129], v219 offset:12288
	s_waitcnt lgkmcnt(1)
	v_mfma_f32_32x32x16_bf16 v[82:97], v[122:125], v[118:121], v[82:97]
	s_waitcnt lgkmcnt(0)
	v_mfma_f32_32x32x16_bf16 v[66:81], v[126:129], v[118:121], v[66:81]
	ds_read_b128 v[118:121], v210 offset:57344
	ds_read_b128 v[122:125], v218 offset:12288
	s_waitcnt lgkmcnt(1)
	v_mfma_f32_32x32x16_bf16 v[82:97], v[118:121], v[114:117], v[82:97]
	s_waitcnt lgkmcnt(0)
	v_mfma_f32_32x32x16_bf16 v[66:81], v[122:125], v[114:117], v[66:81]
	ds_read_b128 v[114:117], v212 offset:57472
	ds_read_b128 v[118:121], v221 offset:12416
	s_waitcnt lgkmcnt(1)
	v_mfma_f32_32x32x16_bf16 v[82:97], v[114:117], v[102:105], v[82:97]
	s_waitcnt lgkmcnt(0)
	v_mfma_f32_32x32x16_bf16 v[66:81], v[118:121], v[102:105], v[66:81]
	ds_read_b128 v[102:105], v213 offset:57472
	ds_read_b128 v[114:117], v220 offset:12416
	s_waitcnt lgkmcnt(1)
	v_mfma_f32_32x32x16_bf16 v[82:97], v[102:105], v[98:101], v[82:97]
	s_waitcnt lgkmcnt(0)
	v_mfma_f32_32x32x16_bf16 v[66:81], v[114:117], v[98:101], v[66:81]
	ds_read_b128 v[98:101], v211 offset:57472
	ds_read_b128 v[102:105], v219 offset:12416
	s_waitcnt lgkmcnt(1)
	v_mfma_f32_32x32x16_bf16 v[82:97], v[98:101], v[110:113], v[82:97]
	s_waitcnt lgkmcnt(0)
	v_mfma_f32_32x32x16_bf16 v[66:81], v[102:105], v[110:113], v[66:81]
	ds_read_b128 v[98:101], v210 offset:57472
	ds_read_b128 v[102:105], v218 offset:12416
	s_waitcnt lgkmcnt(1)
	v_mfma_f32_32x32x16_bf16 v[82:97], v[98:101], v[106:109], v[82:97]
	s_waitcnt lgkmcnt(0)
	v_mfma_f32_32x32x16_bf16 v[66:81], v[102:105], v[106:109], v[66:81]
	ds_read_b128 v[98:101], v212 offset:57600
	ds_read_b128 v[102:105], v221 offset:12544
	ds_read_b128 v[106:109], v209
	s_waitcnt lgkmcnt(0)
	v_mfma_f32_32x32x16_bf16 v[82:97], v[98:101], v[106:109], v[82:97]
	v_mfma_f32_32x32x16_bf16 v[66:81], v[102:105], v[106:109], v[66:81]
	ds_read_b128 v[98:101], v213 offset:57600
	ds_read_b128 v[102:105], v220 offset:12544
	ds_read_b128 v[106:109], v209 offset:1024
	s_waitcnt lgkmcnt(0)
	v_mfma_f32_32x32x16_bf16 v[82:97], v[98:101], v[106:109], v[82:97]
	v_mfma_f32_32x32x16_bf16 v[66:81], v[102:105], v[106:109], v[66:81]
	ds_read_b128 v[98:101], v211 offset:57600
	ds_read_b128 v[102:105], v219 offset:12544
	ds_read_b128 v[106:109], v209 offset:2048
	s_waitcnt lgkmcnt(0)
	v_mfma_f32_32x32x16_bf16 v[82:97], v[98:101], v[106:109], v[82:97]
	v_mfma_f32_32x32x16_bf16 v[66:81], v[102:105], v[106:109], v[66:81]
	ds_read_b128 v[98:101], v210 offset:57600
	ds_read_b128 v[102:105], v218 offset:12544
	ds_read_b128 v[106:109], v209 offset:3072
	s_waitcnt lgkmcnt(0)
	v_mfma_f32_32x32x16_bf16 v[82:97], v[98:101], v[106:109], v[82:97]
	v_mfma_f32_32x32x16_bf16 v[66:81], v[102:105], v[106:109], v[66:81]
	v_add_f32_e32 v0, 0, v150
	v_add_f32_e32 v0, v163, v0
	v_add_f32_e32 v0, v151, v0
	v_add_f32_e32 v0, v161, v0
	v_add_f32_e32 v0, v152, v0
	v_add_f32_e32 v0, v160, v0
	v_add_f32_e32 v0, v153, v0
	v_add_f32_e32 v0, v159, v0
	v_add_f32_e32 v0, v154, v0
	v_add_f32_e32 v0, v158, v0
	v_add_f32_e32 v0, v155, v0
	v_add_f32_e32 v0, v157, v0
	v_exp_f32_e32 v99, v138
	v_add_f32_e32 v0, v148, v0
	v_exp_f32_e32 v108, v139
	v_add_f32_e32 v0, v156, v0
	v_exp_f32_e32 v109, v142
	v_add_f32_e32 v0, v147, v0
	v_exp_f32_e32 v110, v143
	v_add_f32_e32 v0, v149, v0
	v_exp_f32_e32 v111, v130
	v_add_f32_e32 v0, v99, v0
	v_exp_f32_e32 v112, v131
	v_add_f32_e32 v0, v108, v0
	v_exp_f32_e32 v113, v136
	v_add_f32_e32 v0, v109, v0
	v_exp_f32_e32 v114, v137
	v_add_f32_e32 v0, v110, v0
	v_exp_f32_e32 v115, v140
	v_add_f32_e32 v0, v111, v0
	v_exp_f32_e32 v116, v141
	v_add_f32_e32 v0, v112, v0
	v_exp_f32_e32 v117, v144
	v_add_f32_e32 v0, v113, v0
	v_exp_f32_e32 v118, v145
	v_add_f32_e32 v0, v114, v0
	v_exp_f32_e32 v119, v132
	v_add_f32_e32 v0, v115, v0
	v_exp_f32_e32 v120, v133
	v_add_f32_e32 v0, v116, v0
	v_exp_f32_e32 v121, v134
	v_add_f32_e32 v0, v117, v0
	v_exp_f32_e32 v122, v135
	v_add_f32_e32 v0, v118, v0
	v_add_f32_e32 v0, v119, v0
	v_add_f32_e32 v0, v120, v0
	v_add_f32_e32 v0, v121, v0
	v_add_f32_e32 v0, v122, v0
	v_mov_b32_e32 v98, v0
	s_nop 1
	v_permlane32_swap_b32_e32 v0, v98
	v_cvt_pk_bf16_f32 v100, v150, v163
	v_cvt_pk_bf16_f32 v101, v151, v161
	v_cvt_pk_bf16_f32 v102, v152, v160
	v_cvt_pk_bf16_f32 v103, v153, v159
	v_cvt_pk_bf16_f32 v104, v154, v158
	v_cvt_pk_bf16_f32 v105, v155, v157
	v_cvt_pk_bf16_f32 v106, v148, v156
	v_cvt_pk_bf16_f32 v107, v147, v149
	v_cvt_pk_bf16_f32 v108, v99, v108
	v_cvt_pk_bf16_f32 v109, v109, v110
	v_cvt_pk_bf16_f32 v110, v111, v112
	v_cvt_pk_bf16_f32 v111, v113, v114
	v_cvt_pk_bf16_f32 v112, v115, v116
	v_cvt_pk_bf16_f32 v113, v117, v118
	v_cvt_pk_bf16_f32 v114, v119, v120
	v_cvt_pk_bf16_f32 v115, v121, v122
	s_nop 0
	v_permlane32_swap_b32_e32 v100, v102
	v_permlane32_swap_b32_e32 v101, v103
	v_permlane32_swap_b32_e32 v104, v106
	v_permlane32_swap_b32_e32 v105, v107
	v_permlane32_swap_b32_e32 v108, v110
	v_permlane32_swap_b32_e32 v109, v111
	v_permlane32_swap_b32_e32 v112, v114
	v_permlane32_swap_b32_e32 v113, v115
	ds_read_b64_tr_b16 v[116:117], v195 offset:0
	ds_read_b64_tr_b16 v[118:119], v195 offset:0x800
	ds_read_b64_tr_b16 v[120:121], v195 offset:0x1000
	ds_read_b64_tr_b16 v[122:123], v195 offset:0x1800
	ds_read_b64_tr_b16 v[124:125], v195 offset:0x2000
	ds_read_b64_tr_b16 v[126:127], v195 offset:0x2800
	ds_read_b64_tr_b16 v[128:129], v195 offset:0x3000
	ds_read_b64_tr_b16 v[130:131], v195 offset:0x3800
	s_waitcnt lgkmcnt(6)
; __device__ __forceinline__ void mask_tile(f32x16& p0, f32x16& p1, int dq) {
;     const float NEG = -__builtin_inff();
; #pragma unroll
;     for (int r = 0; r < 16; ++r) {
;         const int c = (r & 3) + 8 * (r >> 2);
;         if (dq - c < 0) p0[r] = NEG;
;         if (dq - c - 32 < 0) p1[r] = NEG;
;     }
; }
; template <int VB>
; __device__ __forceinline__ void pv_tile(f32x16* o, int vb0, bf16x8 pa0, bf16x8 pa1, bf16x8 pa2, bf16x8 pa3) {
;     ...
;     PV_D0(0); PV_D0(1); PV_D0(2); PV_D0(3);
	s_nop 0
	v_mfma_f32_32x32x16_bf16 v[50:65], v[100:103], v[116:119], v[50:65]
	ds_read_b64_tr_b16 v[116:117], v195 offset:0x200
	ds_read_b64_tr_b16 v[118:119], v195 offset:0xa00
	s_waitcnt lgkmcnt(6)
	v_mfma_f32_32x32x16_bf16 v[50:65], v[104:107], v[120:123], v[50:65]
	ds_read_b64_tr_b16 v[120:121], v195 offset:0x1200
	ds_read_b64_tr_b16 v[122:123], v195 offset:0x1a00
	s_waitcnt lgkmcnt(6)
	v_mfma_f32_32x32x16_bf16 v[50:65], v[108:111], v[124:127], v[50:65]
	ds_read_b64_tr_b16 v[124:125], v195 offset:0x2200
	ds_read_b64_tr_b16 v[126:127], v195 offset:0x2a00
	s_waitcnt lgkmcnt(6)
	v_mfma_f32_32x32x16_bf16 v[50:65], v[112:115], v[128:131], v[50:65]
	ds_read_b64_tr_b16 v[128:129], v195 offset:0x3200
	ds_read_b64_tr_b16 v[130:131], v195 offset:0x3a00
	s_waitcnt lgkmcnt(0)
	v_mfma_f32_32x32x16_bf16 v[34:49], v[100:103], v[116:119], v[34:49]
	ds_read_b64_tr_b16 v[116:117], v195 offset:0x400
	ds_read_b64_tr_b16 v[118:119], v195 offset:0xc00
	v_mfma_f32_32x32x16_bf16 v[34:49], v[104:107], v[120:123], v[34:49]
	ds_read_b64_tr_b16 v[120:121], v195 offset:0x1400
	ds_read_b64_tr_b16 v[122:123], v195 offset:0x1c00
	v_mfma_f32_32x32x16_bf16 v[34:49], v[108:111], v[124:127], v[34:49]
	ds_read_b64_tr_b16 v[124:125], v195 offset:0x2400
	ds_read_b64_tr_b16 v[126:127], v195 offset:0x2c00
	v_mfma_f32_32x32x16_bf16 v[34:49], v[112:115], v[128:131], v[34:49]
	ds_read_b64_tr_b16 v[128:129], v195 offset:0x3400
	ds_read_b64_tr_b16 v[130:131], v195 offset:0x3c00
	s_waitcnt lgkmcnt(0)
	v_mfma_f32_32x32x16_bf16 v[18:33], v[100:103], v[116:119], v[18:33]
	ds_read_b64_tr_b16 v[116:117], v195 offset:0x600
	ds_read_b64_tr_b16 v[118:119], v195 offset:0xe00
	v_mfma_f32_32x32x16_bf16 v[18:33], v[104:107], v[120:123], v[18:33]
	ds_read_b64_tr_b16 v[120:121], v195 offset:0x1600
	ds_read_b64_tr_b16 v[122:123], v195 offset:0x1e00
	v_mfma_f32_32x32x16_bf16 v[18:33], v[108:111], v[124:127], v[18:33]
	ds_read_b64_tr_b16 v[124:125], v195 offset:0x2600
	ds_read_b64_tr_b16 v[126:127], v195 offset:0x2e00
	v_mfma_f32_32x32x16_bf16 v[18:33], v[112:115], v[128:131], v[18:33]
	ds_read_b64_tr_b16 v[128:129], v195 offset:0x3600
	ds_read_b64_tr_b16 v[130:131], v195 offset:0x3e00
	s_waitcnt lgkmcnt(0)
	v_mfma_f32_32x32x16_bf16 v[2:17], v[100:103], v[116:119], v[2:17]
	s_cmp_lt_i32 s41, 8
	v_mfma_f32_32x32x16_bf16 v[2:17], v[104:107], v[120:123], v[2:17]
	v_mfma_f32_32x32x16_bf16 v[2:17], v[108:111], v[124:127], v[2:17]
	v_mfma_f32_32x32x16_bf16 v[2:17], v[112:115], v[128:131], v[2:17]
	s_cbranch_scc0 .LBB0_546
	v_subrev_u32_e32 v99, s72, v208
	v_add_u32_e32 v99, 64, v99
	v_cmp_gt_i32_e64 s[94:95], 26, v99
	v_cmp_gt_i32_e64 s[96:97], 27, v99
	v_cmp_gt_i32_e64 s[92:93], 25, v99
	s_and_b64 s[94:95], s[96:97], s[94:95]
	v_cmp_gt_i32_e64 s[90:91], 24, v99
	s_and_b64 s[92:93], s[94:95], s[92:93]
	v_cmp_gt_i32_e64 s[88:89], 19, v99
	s_and_b64 s[90:91], s[92:93], s[90:91]
	v_cmp_gt_i32_e64 s[86:87], 18, v99
	s_and_b64 s[88:89], s[90:91], s[88:89]
	v_cmp_gt_i32_e64 s[84:85], 17, v99
	s_and_b64 s[86:87], s[88:89], s[86:87]
	v_cmp_gt_i32_e64 s[82:83], 16, v99
	s_and_b64 s[84:85], s[86:87], s[84:85]
	v_cmp_gt_i32_e64 s[80:81], 11, v99
	s_and_b64 s[82:83], s[84:85], s[82:83]
	v_cmp_gt_i32_e64 s[78:79], 10, v99
	s_and_b64 s[80:81], s[82:83], s[80:81]
	v_cmp_gt_i32_e64 s[76:77], 9, v99
	s_and_b64 s[78:79], s[80:81], s[78:79]
	v_cmp_gt_i32_e64 s[74:75], 8, v99
	s_and_b64 s[76:77], s[78:79], s[76:77]
	v_cmp_gt_i32_e64 s[10:11], 3, v99
	s_and_b64 s[74:75], s[76:77], s[74:75]
	v_cmp_gt_i32_e64 s[8:9], 2, v99
	s_and_b64 s[10:11], s[74:75], s[10:11]
	v_cmp_gt_i32_e64 s[6:7], 1, v99
	s_and_b64 s[8:9], s[10:11], s[8:9]
	v_cmp_gt_i32_e64 s[4:5], 0, v99
	s_and_b64 s[6:7], s[8:9], s[6:7]
	s_and_b64 s[4:5], s[6:7], s[4:5]
	v_cmp_gt_i32_e64 s[70:71], 58, v99
	v_cndmask_b32_e64 v82, v82, v203, s[4:5]
	v_cmp_gt_i32_e64 s[4:5], 59, v99
	v_cmp_gt_i32_e64 s[68:69], 57, v99
	v_cmp_gt_i32_e64 s[66:67], 56, v99
	v_cndmask_b32_e64 v81, v81, v203, s[4:5]
	s_and_b64 s[4:5], s[4:5], s[70:71]
	v_cndmask_b32_e64 v80, v80, v203, s[4:5]
	s_and_b64 s[4:5], s[4:5], s[68:69]
	v_cmp_gt_i32_e64 s[64:65], 51, v99
	v_cndmask_b32_e64 v79, v79, v203, s[4:5]
	s_and_b64 s[4:5], s[4:5], s[66:67]
	v_cmp_gt_i32_e64 s[62:63], 50, v99
	v_cndmask_b32_e64 v78, v78, v203, s[4:5]
	s_and_b64 s[4:5], s[4:5], s[64:65]
	v_cmp_gt_i32_e64 s[60:61], 49, v99
	v_cndmask_b32_e64 v77, v77, v203, s[4:5]
	s_and_b64 s[4:5], s[4:5], s[62:63]
	v_cmp_gt_i32_e64 s[58:59], 48, v99
	v_cndmask_b32_e64 v76, v76, v203, s[4:5]
	s_and_b64 s[4:5], s[4:5], s[60:61]
	v_cmp_gt_i32_e64 s[56:57], 43, v99
	v_cndmask_b32_e64 v75, v75, v203, s[4:5]
	s_and_b64 s[4:5], s[4:5], s[58:59]
	v_cmp_gt_i32_e64 s[54:55], 42, v99
	v_cndmask_b32_e64 v74, v74, v203, s[4:5]
	s_and_b64 s[4:5], s[4:5], s[56:57]
	v_cmp_gt_i32_e64 s[52:53], 41, v99
	v_cndmask_b32_e64 v73, v73, v203, s[4:5]
	s_and_b64 s[4:5], s[4:5], s[54:55]
	v_cmp_gt_i32_e64 s[50:51], 40, v99
	v_cndmask_b32_e64 v72, v72, v203, s[4:5]
	s_and_b64 s[4:5], s[4:5], s[52:53]
	v_cmp_gt_i32_e64 s[48:49], 35, v99
	v_cndmask_b32_e64 v71, v71, v203, s[4:5]
	s_and_b64 s[4:5], s[4:5], s[50:51]
	v_cmp_gt_i32_e64 s[46:47], 34, v99
	v_cndmask_b32_e64 v70, v70, v203, s[4:5]
	s_and_b64 s[4:5], s[4:5], s[48:49]
	v_cmp_gt_i32_e64 s[44:45], 33, v99
	v_cndmask_b32_e64 v69, v69, v203, s[4:5]
	s_and_b64 s[4:5], s[4:5], s[46:47]
	v_cmp_gt_i32_e32 vcc, 32, v99
	v_cndmask_b32_e64 v68, v68, v203, s[4:5]
	s_and_b64 s[4:5], s[4:5], s[44:45]
	s_and_b64 vcc, s[4:5], vcc
	v_cndmask_b32_e64 v97, v97, v203, s[96:97]
	v_cndmask_b32_e64 v96, v96, v203, s[94:95]
	v_cndmask_b32_e64 v95, v95, v203, s[92:93]
	v_cndmask_b32_e64 v94, v94, v203, s[90:91]
	v_cndmask_b32_e64 v93, v93, v203, s[88:89]
	v_cndmask_b32_e64 v92, v92, v203, s[86:87]
	v_cndmask_b32_e64 v91, v91, v203, s[84:85]
	v_cndmask_b32_e64 v90, v90, v203, s[82:83]
	v_cndmask_b32_e64 v89, v89, v203, s[80:81]
	v_cndmask_b32_e64 v88, v88, v203, s[78:79]
	v_cndmask_b32_e64 v87, v87, v203, s[76:77]
	v_cndmask_b32_e64 v86, v86, v203, s[74:75]
	v_cndmask_b32_e64 v85, v85, v203, s[10:11]
	v_cndmask_b32_e64 v84, v84, v203, s[8:9]
	v_cndmask_b32_e64 v83, v83, v203, s[6:7]
	v_cndmask_b32_e64 v67, v67, v203, s[4:5]
	v_cndmask_b32_e32 v66, v66, v203, vcc

; __device__ __forceinline__ void partialSM(f32x16& p0, f32x16& p1, float& m_reg, float& mn, float& alpha) {
;     ...
;     for (int r = 0; r < 16; ++r) p0[r] = p0[r] - mn;
; #pragma unroll
;     for (int r = 0; r < 16; ++r) p1[r] = p1[r] - mn;
; #pragma unroll
;     for (int r = 0; r < 16; ++r) p0[r] = __builtin_amdgcn_exp2f(p0[r]);
; }
; __device__ __forceinline__ void finishSM(f32x16& p0, f32x16& p1, float alpha, float& l_reg, bf16x8& pa0, bf16x8& pa1, bf16x8& pa2, bf16x8& pa3) {
; #pragma unroll
;     for (int r = 0; r < 16; ++r) p1[r] = __builtin_amdgcn_exp2f(p1[r]);
;     float ps = 0;
; #pragma unroll
;     for (int r = 0; r < 16; ++r) ps += p0[r];
; #pragma unroll
;     for (int r = 0; r < 16; ++r) ps += p1[r];
;     { auto rr = __builtin_amdgcn_permlane32_swap(__float_as_uint(ps), __float_as_uint(ps), false, false);
;       ps = __uint_as_float(rr[0]) + __uint_as_float(rr[1]); }
;     l_reg = l_reg * alpha + ps;
;     ...
;     PK4(p0, 0, pa0); PK4(p0, 8, pa1); PK4(p1, 0, pa2); PK4(p1, 8, pa3);
; template <int VB>
; __device__ __forceinline__ void pv_tile(f32x16* o, int vb0, bf16x8 pa0, bf16x8 pa1, bf16x8 pa2, bf16x8 pa3) {
;     ...
;     PV_D0(0); PV_D0(1); PV_D0(2); PV_D0(3);
.LBB0_550:
	v_cndmask_b32_e64 v100, v100, v162, s[44:45]
	v_sub_f32_e32 v82, v82, v100
	v_sub_f32_e32 v83, v83, v100
	v_exp_f32_e32 v82, v82
	v_sub_f32_e32 v84, v84, v100
	v_exp_f32_e32 v83, v83
	v_sub_f32_e32 v85, v85, v100
	v_exp_f32_e32 v84, v84
	v_sub_f32_e32 v86, v86, v100
	v_sub_f32_e32 v66, v66, v100
	v_exp_f32_e32 v85, v85
	v_sub_f32_e32 v87, v87, v100
	v_sub_f32_e32 v88, v88, v100
	v_sub_f32_e32 v89, v89, v100
	v_sub_f32_e32 v90, v90, v100
	v_sub_f32_e32 v91, v91, v100
	v_sub_f32_e32 v92, v92, v100
	v_sub_f32_e32 v93, v93, v100
	v_sub_f32_e32 v94, v94, v100
	v_sub_f32_e32 v95, v95, v100
	v_sub_f32_e32 v96, v96, v100
	v_sub_f32_e32 v97, v97, v100
	v_sub_f32_e32 v67, v67, v100
	v_sub_f32_e32 v68, v68, v100
	v_sub_f32_e32 v69, v69, v100
	v_sub_f32_e32 v70, v70, v100
	v_sub_f32_e32 v71, v71, v100
	v_sub_f32_e32 v72, v72, v100
	v_sub_f32_e32 v73, v73, v100
	v_sub_f32_e32 v74, v74, v100
	v_sub_f32_e32 v75, v75, v100
	v_sub_f32_e32 v76, v76, v100
	v_sub_f32_e32 v77, v77, v100
	v_sub_f32_e32 v78, v78, v100
	v_sub_f32_e32 v79, v79, v100
	v_sub_f32_e32 v80, v80, v100
	v_sub_f32_e32 v81, v81, v100
	v_exp_f32_e32 v86, v86
	v_exp_f32_e32 v100, v66
	v_add_f32_e32 v66, 0, v82
	v_exp_f32_e32 v87, v87
	v_add_f32_e32 v66, v83, v66
	v_exp_f32_e32 v88, v88
	v_add_f32_e32 v66, v84, v66
	v_exp_f32_e32 v89, v89
	v_add_f32_e32 v66, v85, v66
	v_exp_f32_e32 v90, v90
	v_add_f32_e32 v66, v86, v66
	v_exp_f32_e32 v91, v91
	v_add_f32_e32 v66, v87, v66
	v_exp_f32_e32 v92, v92
	v_add_f32_e32 v66, v88, v66
	v_exp_f32_e32 v93, v93
	v_add_f32_e32 v66, v89, v66
	v_exp_f32_e32 v94, v94
	v_add_f32_e32 v66, v90, v66
	v_exp_f32_e32 v95, v95
	v_add_f32_e32 v66, v91, v66
	v_exp_f32_e32 v96, v96
	v_add_f32_e32 v66, v92, v66
	v_exp_f32_e32 v97, v97
	v_add_f32_e32 v66, v93, v66
	v_add_f32_e32 v66, v94, v66
	v_exp_f32_e32 v101, v67
	v_add_f32_e32 v66, v95, v66
	v_exp_f32_e32 v102, v68
	v_add_f32_e32 v66, v96, v66
	v_exp_f32_e32 v103, v69
	v_add_f32_e32 v66, v97, v66
	v_exp_f32_e32 v104, v70
	v_add_f32_e32 v66, v100, v66
	v_exp_f32_e32 v105, v71
	v_add_f32_e32 v66, v101, v66
	v_exp_f32_e32 v106, v72
	v_add_f32_e32 v66, v102, v66
	v_exp_f32_e32 v107, v73
	v_add_f32_e32 v66, v103, v66
	v_exp_f32_e32 v108, v74
	v_add_f32_e32 v66, v104, v66
	v_exp_f32_e32 v109, v75
	v_add_f32_e32 v66, v105, v66
	v_exp_f32_e32 v110, v76
	v_add_f32_e32 v66, v106, v66
	v_exp_f32_e32 v111, v77
	v_add_f32_e32 v66, v107, v66
	v_exp_f32_e32 v112, v78
	v_add_f32_e32 v66, v108, v66
	v_exp_f32_e32 v113, v79
	v_add_f32_e32 v66, v109, v66
	v_exp_f32_e32 v114, v80
	v_add_f32_e32 v66, v110, v66
	v_exp_f32_e32 v115, v81
	v_add_f32_e32 v66, v111, v66
	v_add_f32_e32 v66, v112, v66
	v_add_f32_e32 v66, v113, v66
	v_add_f32_e32 v66, v114, v66
	v_add_f32_e32 v66, v115, v66
	v_mov_b32_e32 v67, v66
	s_nop 1
	v_permlane32_swap_b32_e32 v66, v67
	v_cvt_pk_bf16_f32 v68, v82, v83
	v_cvt_pk_bf16_f32 v69, v84, v85
	v_cvt_pk_bf16_f32 v70, v86, v87
	v_cvt_pk_bf16_f32 v71, v88, v89
	v_cvt_pk_bf16_f32 v72, v90, v91
	v_cvt_pk_bf16_f32 v73, v92, v93
	v_cvt_pk_bf16_f32 v74, v94, v95
	v_cvt_pk_bf16_f32 v75, v96, v97
	v_cvt_pk_bf16_f32 v76, v100, v101
	v_cvt_pk_bf16_f32 v77, v102, v103
	v_cvt_pk_bf16_f32 v78, v104, v105
	v_cvt_pk_bf16_f32 v79, v106, v107
	v_cvt_pk_bf16_f32 v80, v108, v109
	v_cvt_pk_bf16_f32 v81, v110, v111
	v_cvt_pk_bf16_f32 v82, v112, v113
	v_cvt_pk_bf16_f32 v83, v114, v115
	s_nop 0
	v_permlane32_swap_b32_e32 v68, v70
	v_permlane32_swap_b32_e32 v69, v71
	v_permlane32_swap_b32_e32 v72, v74
	v_permlane32_swap_b32_e32 v73, v75
	v_permlane32_swap_b32_e32 v76, v78
	v_permlane32_swap_b32_e32 v77, v79
	v_permlane32_swap_b32_e32 v80, v82
	v_permlane32_swap_b32_e32 v81, v83
	ds_read_b64_tr_b16 v[84:85], v195 offset:0x4000
	ds_read_b64_tr_b16 v[86:87], v195 offset:0x4800
	ds_read_b64_tr_b16 v[88:89], v195 offset:0x5000
	ds_read_b64_tr_b16 v[90:91], v195 offset:0x5800
	ds_read_b64_tr_b16 v[92:93], v195 offset:0x6000
	ds_read_b64_tr_b16 v[94:95], v195 offset:0x6800
	ds_read_b64_tr_b16 v[100:101], v195 offset:0x7000
	ds_read_b64_tr_b16 v[102:103], v195 offset:0x7800
	s_waitcnt lgkmcnt(6)
	s_nop 0
	v_mfma_f32_32x32x16_bf16 v[50:65], v[68:71], v[84:87], v[50:65]
	ds_read_b64_tr_b16 v[84:85], v195 offset:0x4200
	ds_read_b64_tr_b16 v[86:87], v195 offset:0x4a00
	s_waitcnt lgkmcnt(6)
	v_mfma_f32_32x32x16_bf16 v[50:65], v[72:75], v[88:91], v[50:65]
	ds_read_b64_tr_b16 v[88:89], v195 offset:0x5200
	ds_read_b64_tr_b16 v[90:91], v195 offset:0x5a00
	s_waitcnt lgkmcnt(6)
	v_mfma_f32_32x32x16_bf16 v[50:65], v[76:79], v[92:95], v[50:65]
	ds_read_b64_tr_b16 v[92:93], v195 offset:0x6200
	ds_read_b64_tr_b16 v[94:95], v195 offset:0x6a00
	s_waitcnt lgkmcnt(6)
	v_mfma_f32_32x32x16_bf16 v[50:65], v[80:83], v[100:103], v[50:65]
	ds_read_b64_tr_b16 v[100:101], v195 offset:0x7200
	ds_read_b64_tr_b16 v[102:103], v195 offset:0x7a00
	s_waitcnt lgkmcnt(0)
	v_mfma_f32_32x32x16_bf16 v[34:49], v[68:71], v[84:87], v[34:49]
	ds_read_b64_tr_b16 v[84:85], v195 offset:0x4400
	ds_read_b64_tr_b16 v[86:87], v195 offset:0x4c00
	v_mfma_f32_32x32x16_bf16 v[34:49], v[72:75], v[88:91], v[34:49]
	ds_read_b64_tr_b16 v[88:89], v195 offset:0x5400
	ds_read_b64_tr_b16 v[90:91], v195 offset:0x5c00
	v_mfma_f32_32x32x16_bf16 v[34:49], v[76:79], v[92:95], v[34:49]
	ds_read_b64_tr_b16 v[92:93], v195 offset:0x6400
	ds_read_b64_tr_b16 v[94:95], v195 offset:0x6c00
	v_mfma_f32_32x32x16_bf16 v[34:49], v[80:83], v[100:103], v[34:49]
	ds_read_b64_tr_b16 v[100:101], v195 offset:0x7400
	ds_read_b64_tr_b16 v[102:103], v195 offset:0x7c00
	s_waitcnt lgkmcnt(0)
	v_mfma_f32_32x32x16_bf16 v[18:33], v[68:71], v[84:87], v[18:33]
	ds_read_b64_tr_b16 v[84:85], v195 offset:0x4600
	ds_read_b64_tr_b16 v[86:87], v195 offset:0x4e00
	v_mfma_f32_32x32x16_bf16 v[18:33], v[72:75], v[88:91], v[18:33]
	ds_read_b64_tr_b16 v[88:89], v195 offset:0x5600
	ds_read_b64_tr_b16 v[90:91], v195 offset:0x5e00
	v_mfma_f32_32x32x16_bf16 v[18:33], v[76:79], v[92:95], v[18:33]
	ds_read_b64_tr_b16 v[92:93], v195 offset:0x6600
	ds_read_b64_tr_b16 v[94:95], v195 offset:0x6e00
	v_mfma_f32_32x32x16_bf16 v[18:33], v[80:83], v[100:103], v[18:33]
	ds_read_b64_tr_b16 v[100:101], v195 offset:0x7600
	ds_read_b64_tr_b16 v[102:103], v195 offset:0x7e00
	s_waitcnt lgkmcnt(0)
	v_mfma_f32_32x32x16_bf16 v[2:17], v[68:71], v[84:87], v[2:17]
	v_mfma_f32_32x32x16_bf16 v[2:17], v[72:75], v[88:91], v[2:17]
	v_mfma_f32_32x32x16_bf16 v[2:17], v[76:79], v[92:95], v[2:17]
	v_mfma_f32_32x32x16_bf16 v[2:17], v[80:83], v[100:103], v[2:17]
	s_barrier
; __device__ __forceinline__ float lane_xor1(float v) { return __builtin_bit_cast(float, __builtin_amdgcn_update_dpp(0, __builtin_bit_cast(int, v), 0xB1, 0xF, 0xF, false)); }
; __device__ __forceinline__ int crow(int r, int hi) { return (r & 3) + 8 * (r >> 2) + 4 * hi; }
; __device__ __forceinline__ unsigned cvtpk(float lo, float hi) { unsigned r; asm volatile("v_cvt_pk_bf16_f32 %0, %1, %2" : "=v"(r) : "v"(lo), "v"(hi)); return r; }
; template <bool MLA, int MODE, bool PIPE>
; __device__ __forceinline__ void attn_block(const AttnArgs& a, char* lds) {
;     ...
;     if (hi == 0) li_l[r32] = l_reg; asm volatile("s_waitcnt lgkmcnt(0)" ::: "memory");
;     float rli[16];
; #pragma unroll
;     for (int r = 0; r < 16; ++r) rli[r] = __builtin_amdgcn_rcpf(li_l[crow(r, hi)]);
;     if constexpr (MODE == 0) {
;         bf16_t* Ow = a.Out + (size_t)qlo * 1024;
; #pragma unroll
;         for (int r = 0; r < 16; ++r) { const int orow = crow(r, hi);
; #pragma unroll
;             for (int d0 = 0; d0 < 4; ++d0) { const float v = o[d0][r] * rli[r]; const float vn = lane_xor1(v);
;                 if ((r32 & 1) == 0) *(unsigned*)(Ow + (size_t)orow * 1024 + d0 * 32 + r32) = cvtpk(v, vn); } }
	s_and_saveexec_b64 s[4:5], s[42:43]
	v_add_f32_e32 v0, v0, v98
	v_fmac_f32_e32 v0, v207, v146
	v_add_f32_e32 v66, v66, v67
	v_fmac_f32_e32 v66, v0, v99
	ds_write_b32 v197, v66
	s_or_b64 exec, exec, s[4:5]
	v_readlane_b32 s4, v254, 53
	s_add_u32 s3, s14, s24
	v_readlane_b32 s5, v254, 54
	s_addc_u32 s6, s15, s25
	s_lshl_b64 s[4:5], s[4:5], 1
	s_waitcnt lgkmcnt(0)
	s_add_u32 s3, s3, s4
	ds_read_b128 v[78:81], v196
	ds_read_b128 v[74:77], v196 offset:32
	s_addc_u32 s4, s6, s5
	v_readlane_b32 s5, v254, 55
	s_lshl_b32 s5, s5, 1
	s_add_u32 s5, s3, s5
	s_addc_u32 s4, s4, 0
	s_ashr_i32 s3, s2, 31
	s_waitcnt lgkmcnt(1)
	v_rcp_f32_e32 v78, v78
	s_lshl_b64 s[2:3], s[2:3], 11
	ds_read_b128 v[70:73], v196 offset:64
	ds_read_b128 v[66:69], v196 offset:96
	s_add_u32 s2, s5, s2
	v_and_b32_e32 v0, 1, v193
	s_addc_u32 s3, s4, s3
	v_cmp_eq_u32_e64 s[42:43], 0, v0
	v_lshlrev_b32_e32 v0, 1, v194
	v_lshl_add_u64 v[82:83], s[2:3], 0, v[0:1]
	v_lshlrev_b32_e32 v0, 13, v192
	v_lshl_add_u64 v[82:83], v[82:83], 0, v[0:1]
	s_mov_b64 s[2:3], 0x20c00000
	v_mul_f32_e32 v0, v50, v78
	v_mov_b32_e32 v50, v1
	v_lshl_add_u64 v[82:83], v[82:83], 0, s[2:3]
	s_nop 0
	v_mov_b32_dpp v50, v0 quad_perm:[1,0,3,2] row_mask:0xf bank_mask:0xf
	s_and_saveexec_b64 s[2:3], s[42:43]
	s_cbranch_execz .LBB0_554
	v_cvt_pk_bf16_f32 v0, v0, v50
	global_store_dword v[82:83], v0, off

; __device__ __forceinline__ void finishSM(f32x16& p0, f32x16& p1, float alpha, float& l_reg, bf16x8& pa0, bf16x8& pa1, bf16x8& pa2, bf16x8& pa3) {
; #pragma unroll
;     for (int r = 0; r < 16; ++r) p1[r] = __builtin_amdgcn_exp2f(p1[r]);
;     float ps = 0;
; #pragma unroll
;     for (int r = 0; r < 16; ++r) ps += p0[r];
; #pragma unroll
;     for (int r = 0; r < 16; ++r) ps += p1[r];
;     { auto rr = __builtin_amdgcn_permlane32_swap(__float_as_uint(ps), __float_as_uint(ps), false, false);
;       ps = __uint_as_float(rr[0]) + __uint_as_float(rr[1]); }
;     l_reg = l_reg * alpha + ps;
;     ...
;     PK4(p0, 0, pa0); PK4(p0, 8, pa1); PK4(p1, 0, pa2); PK4(p1, 8, pa3);
; template <int KB, int DQK>
; __device__ __forceinline__ void qkt(f32x16& p0, f32x16& p1, const char* K_lds, int r32, int hi, const bf16x8* qr, const char* qrl) {
;     constexpr int SHMK = 64 * DQK * 2, NF = DQK / 16, NFR = NF > 8 ? 8 : NF;
;     p0 = f32x16{}; p1 = f32x16{};
;     const char* kb[4];
; #pragma unroll
;     for (int dd = 0; dd < 4; ++dd) kb[dd] = K_lds + KB * SHMK + kswz<DQK>(r32, (dd * 16 + hi * 8) * 2);
; #pragma unroll
;     for (int d0 = 0; d0 < NF; ++d0) { const char* a = kb[d0 & 3] + (d0 >> 2) * 128;
;         bf16x8 b0 = *reinterpret_cast<const bf16x8*>(a);
;         bf16x8 b1 = *reinterpret_cast<const bf16x8*>(a + 32 * DQK * 2);
;         bf16x8 q; if (d0 < NFR) q = qr[d0]; else q = *reinterpret_cast<const bf16x8*>(qrl + (d0 - NFR) * 1024);
;         p0 = __builtin_amdgcn_mfma_f32_32x32x16_bf16(b0, q, p0, 0, 0, 0);
;         p1 = __builtin_amdgcn_mfma_f32_32x32x16_bf16(b1, q, p1, 0, 0, 0); }
.LBB0_693:
	ds_read_b128 v[66:69], v161 offset:40960
	ds_read_b128 v[70:73], v161 offset:45056
	v_add_f32_e32 v0, 0, v149
	v_add_f32_e32 v0, v186, v0
	v_add_f32_e32 v0, v147, v0
	s_waitcnt lgkmcnt(1)
	v_mfma_f32_32x32x16_bf16 v[82:97], v[66:69], v[110:113], 0
	v_add_f32_e32 v0, v183, v0
	v_add_f32_e32 v0, v141, v0
	ds_read_b128 v[188:191], v162 offset:40960
	ds_read_b128 v[192:195], v162 offset:45056
	v_add_f32_e32 v0, v148, v0
	v_add_f32_e32 v0, v140, v0
	v_add_f32_e32 v0, v146, v0
	v_add_f32_e32 v0, v137, v0
	s_waitcnt lgkmcnt(2)
	v_mfma_f32_32x32x16_bf16 v[66:81], v[70:73], v[110:113], 0
	v_add_f32_e32 v0, v139, v0
	v_add_f32_e32 v0, v135, v0
	v_add_f32_e32 v0, v138, v0
	v_exp_f32_e32 v122, v122
	v_add_f32_e32 v0, v133, v0
	v_exp_f32_e32 v123, v123
	v_add_f32_e32 v0, v136, v0
	s_waitcnt lgkmcnt(1)
	v_mfma_f32_32x32x16_bf16 v[82:97], v[188:191], v[106:109], v[82:97]
	v_exp_f32_e32 v131, v126
	v_add_f32_e32 v0, v132, v0
	v_exp_f32_e32 v167, v127
	v_add_f32_e32 v0, v134, v0
	v_exp_f32_e32 v114, v114
	v_add_f32_e32 v0, v122, v0
	v_exp_f32_e32 v115, v115
	s_waitcnt lgkmcnt(0)
	v_mfma_f32_32x32x16_bf16 v[66:81], v[192:195], v[106:109], v[66:81]
	ds_read_b128 v[188:191], v163 offset:40960
	ds_read_b128 v[192:195], v163 offset:45056
	v_add_f32_e32 v0, v123, v0
	v_exp_f32_e32 v120, v120
	v_add_f32_e32 v0, v131, v0
	v_exp_f32_e32 v121, v121
	v_add_f32_e32 v0, v167, v0
	v_exp_f32_e32 v124, v124
	s_waitcnt lgkmcnt(1)
	v_mfma_f32_32x32x16_bf16 v[82:97], v[188:191], v[102:105], v[82:97]
	v_add_f32_e32 v0, v114, v0
	v_exp_f32_e32 v125, v125
	v_add_f32_e32 v0, v115, v0
	v_exp_f32_e32 v170, v128
	v_add_f32_e32 v0, v120, v0
	v_exp_f32_e32 v171, v129
	v_add_f32_e32 v0, v121, v0
	s_waitcnt lgkmcnt(0)
	v_mfma_f32_32x32x16_bf16 v[66:81], v[192:195], v[102:105], v[66:81]
	ds_read_b128 v[188:191], v164 offset:40960
	ds_read_b128 v[192:195], v164 offset:45056
	v_exp_f32_e32 v116, v116
	v_add_f32_e32 v0, v124, v0
	v_exp_f32_e32 v117, v117
	v_add_f32_e32 v0, v125, v0
	v_exp_f32_e32 v118, v118
	v_add_f32_e32 v0, v170, v0
	s_waitcnt lgkmcnt(1)
	v_mfma_f32_32x32x16_bf16 v[82:97], v[188:191], v[98:101], v[82:97]
	v_exp_f32_e32 v119, v119
	v_add_f32_e32 v0, v171, v0
	v_add_f32_e32 v0, v116, v0
	v_add_f32_e32 v0, v117, v0
	v_add_f32_e32 v0, v118, v0
	v_add_f32_e32 v0, v119, v0
	v_mov_b32_e32 v181, v0
	s_waitcnt lgkmcnt(0)
	v_mfma_f32_32x32x16_bf16 v[66:81], v[192:195], v[98:101], v[66:81]
	v_cvt_pk_bf16_f32 v126, v149, v186
	v_cvt_pk_bf16_f32 v127, v147, v183
	v_cvt_pk_bf16_f32 v128, v141, v148
	v_permlane32_swap_b32_e32 v0, v181
	v_cvt_pk_bf16_f32 v129, v140, v146
	v_permlane32_swap_b32_e32 v126, v128
	v_cvt_pk_bf16_f32 v182, v137, v139
	v_cvt_pk_bf16_f32 v183, v135, v138
	v_cvt_pk_bf16_f32 v184, v133, v136
	v_cvt_pk_bf16_f32 v185, v132, v134
	v_cvt_pk_bf16_f32 v132, v122, v123
	v_cvt_pk_bf16_f32 v133, v131, v167
	v_cvt_pk_bf16_f32 v134, v114, v115
	v_cvt_pk_bf16_f32 v135, v120, v121
	v_cvt_pk_bf16_f32 v136, v124, v125
	v_cvt_pk_bf16_f32 v137, v170, v171
	v_cvt_pk_bf16_f32 v138, v116, v117
	v_cvt_pk_bf16_f32 v139, v118, v119
	v_permlane32_swap_b32_e32 v127, v129
	v_permlane32_swap_b32_e32 v182, v184
	v_permlane32_swap_b32_e32 v183, v185
	v_permlane32_swap_b32_e32 v132, v134
	v_permlane32_swap_b32_e32 v133, v135
	v_permlane32_swap_b32_e32 v136, v138
	v_permlane32_swap_b32_e32 v137, v139
	v_lshl_add_u64 v[146:147], v[142:143], 0, s[26:27]
	v_add_co_u32_e32 v114, vcc, s20, v146
	s_mov_b32 s4, 0x18cb4000
	s_nop 0
	v_addc_co_u32_e32 v115, vcc, 0, v147, vcc
	v_add_co_u32_e32 v118, vcc, s4, v146
	v_lshl_add_u64 v[148:149], v[144:145], 0, s[26:27]
	s_nop 0
	v_addc_co_u32_e32 v119, vcc, 0, v147, vcc
	v_add_co_u32_e32 v122, vcc, s20, v148
	global_load_dwordx4 v[114:117], v[114:115], off offset:3456
	s_nop 0
	global_load_dwordx4 v[118:121], v[118:119], off offset:3456
	v_addc_co_u32_e32 v123, vcc, 0, v149, vcc
	global_load_dwordx4 v[122:125], v[122:123], off offset:2432
	ds_read_b64_tr_b16 v[186:187], v153 offset:0
	ds_read_b64_tr_b16 v[188:189], v153 offset:0x800
	ds_read_b64_tr_b16 v[190:191], v153 offset:0x1000
	ds_read_b64_tr_b16 v[192:193], v153 offset:0x1800
	ds_read_b64_tr_b16 v[194:195], v153 offset:0x2000
	ds_read_b64_tr_b16 v[196:197], v153 offset:0x2800
	ds_read_b64_tr_b16 v[208:209], v153 offset:0x3000
	ds_read_b64_tr_b16 v[210:211], v153 offset:0x3800
	s_waitcnt lgkmcnt(6)
	s_nop 0
	v_mfma_f32_32x32x16_bf16 v[50:65], v[126:129], v[186:189], v[50:65]
	ds_read_b64_tr_b16 v[186:187], v153 offset:0x200
	ds_read_b64_tr_b16 v[188:189], v153 offset:0xa00
	s_waitcnt lgkmcnt(6)
	v_mfma_f32_32x32x16_bf16 v[50:65], v[182:185], v[190:193], v[50:65]
	ds_read_b64_tr_b16 v[190:191], v153 offset:0x1200
	ds_read_b64_tr_b16 v[192:193], v153 offset:0x1a00
	s_waitcnt lgkmcnt(6)
	v_mfma_f32_32x32x16_bf16 v[50:65], v[132:135], v[194:197], v[50:65]
	ds_read_b64_tr_b16 v[194:195], v153 offset:0x2200
	ds_read_b64_tr_b16 v[196:197], v153 offset:0x2a00
	s_waitcnt lgkmcnt(6)
	v_mfma_f32_32x32x16_bf16 v[50:65], v[136:139], v[208:211], v[50:65]
	ds_read_b64_tr_b16 v[208:209], v153 offset:0x3200
	ds_read_b64_tr_b16 v[210:211], v153 offset:0x3a00
	s_waitcnt lgkmcnt(0)
	v_mfma_f32_32x32x16_bf16 v[34:49], v[126:129], v[186:189], v[34:49]
	ds_read_b64_tr_b16 v[186:187], v153 offset:0x400
	ds_read_b64_tr_b16 v[188:189], v153 offset:0xc00
	v_mfma_f32_32x32x16_bf16 v[34:49], v[182:185], v[190:193], v[34:49]
	ds_read_b64_tr_b16 v[190:191], v153 offset:0x1400
	ds_read_b64_tr_b16 v[192:193], v153 offset:0x1c00
	v_mfma_f32_32x32x16_bf16 v[34:49], v[132:135], v[194:197], v[34:49]
	ds_read_b64_tr_b16 v[194:195], v153 offset:0x2400
	ds_read_b64_tr_b16 v[196:197], v153 offset:0x2c00
	v_mfma_f32_32x32x16_bf16 v[34:49], v[136:139], v[208:211], v[34:49]
	ds_read_b64_tr_b16 v[208:209], v153 offset:0x3400
	ds_read_b64_tr_b16 v[210:211], v153 offset:0x3c00
	s_waitcnt lgkmcnt(0)
	v_mfma_f32_32x32x16_bf16 v[18:33], v[126:129], v[186:189], v[18:33]
	ds_read_b64_tr_b16 v[186:187], v153 offset:0x600
	ds_read_b64_tr_b16 v[188:189], v153 offset:0xe00
	v_mfma_f32_32x32x16_bf16 v[18:33], v[182:185], v[190:193], v[18:33]
	ds_read_b64_tr_b16 v[190:191], v153 offset:0x1600
	ds_read_b64_tr_b16 v[192:193], v153 offset:0x1e00
	v_mfma_f32_32x32x16_bf16 v[18:33], v[132:135], v[194:197], v[18:33]
	ds_read_b64_tr_b16 v[194:195], v153 offset:0x2600
	ds_read_b64_tr_b16 v[196:197], v153 offset:0x2e00
	v_mfma_f32_32x32x16_bf16 v[18:33], v[136:139], v[208:211], v[18:33]
	ds_read_b64_tr_b16 v[208:209], v153 offset:0x3600
	ds_read_b64_tr_b16 v[210:211], v153 offset:0x3e00
	s_waitcnt lgkmcnt(0)
	v_mfma_f32_32x32x16_bf16 v[2:17], v[126:129], v[186:189], v[2:17]
	s_add_i32 s4, s21, 49
	s_cmp_le_i32 s4, s30
	v_add_u32_e32 v126, 0x5b, v180
	v_mfma_f32_32x32x16_bf16 v[2:17], v[182:185], v[190:193], v[2:17]
	v_mfma_f32_32x32x16_bf16 v[2:17], v[132:135], v[194:197], v[2:17]
	v_mfma_f32_32x32x16_bf16 v[2:17], v[136:139], v[208:211], v[2:17]
	s_cbranch_scc1 .LBB0_695
; __device__ __forceinline__ void bias_tile(f32x16& p0, f32x16& p1, int dq, const float* tb) {
; #pragma unroll
;     for (int r = 0; r < 16; ++r) {
;         const int c = (r & 3) + 8 * (r >> 2);
;         int d0 = dq - c, d1 = dq - c - 32;
;         d0 = d0 < 0 ? 0 : (d0 > 127 ? 127 : d0); d1 = d1 < 0 ? 0 : (d1 > 127 ? 127 : d1);
;         p0[r] += tb[d0]; p1[r] += tb[d1];
;     }
; }
	v_med3_i32 v128, v126, 32, v206
	v_lshl_add_u32 v128, v128, 2, s33
	v_add_u32_e32 v129, 0xffffff80, v128
	v_add_u32_e32 v128, 0x5a, v180
	v_med3_i32 v131, v128, 0, v205
	v_med3_i32 v128, v128, 32, v206
	v_lshl_add_u32 v128, v128, 2, s33
	v_add_u32_e32 v133, 0xffffff80, v128
	v_add_u32_e32 v128, 0x59, v180
	v_med3_i32 v132, v128, 0, v205
	v_med3_i32 v128, v128, 32, v206
	v_lshl_add_u32 v128, v128, 2, s33
	v_add_u32_e32 v135, 0xffffff80, v128
	v_add_u32_e32 v128, 0x58, v180
	v_lshl_add_u32 v134, v132, 2, s33
	v_med3_i32 v132, v128, 0, v205
	v_med3_i32 v128, v128, 32, v206
	v_med3_i32 v127, v126, 0, v205
	v_lshl_add_u32 v128, v128, 2, s33
	v_lshl_add_u32 v127, v127, 2, s33
	v_lshl_add_u32 v137, v132, 2, s33
	v_add_u32_e32 v138, 0xffffff80, v128
	v_lshl_add_u32 v131, v131, 2, s33
	ds_read_b32 v128, v127
	ds_read_b32 v132, v129
	ds_read_b32 v129, v131
	ds_read_b32 v133, v133
	ds_read_b32 v134, v134
	ds_read_b32 v136, v135
	ds_read_b32 v135, v137
	ds_read_b32 v137, v138
	v_add_u32_e32 v138, 0x52, v180
	v_med3_i32 v139, v138, 0, v205
	v_med3_i32 v138, v138, 32, v206
	v_lshl_add_u32 v138, v138, 2, s33
	v_add_u32_e32 v141, 0xffffff80, v138
	v_add_u32_e32 v138, 0x51, v180
	v_med3_i32 v140, v138, 0, v205
	v_med3_i32 v138, v138, 32, v206
	v_add_u32_e32 v127, 0x53, v180
	v_lshl_add_u32 v138, v138, 2, s33
	v_med3_i32 v131, v127, 0, v205
	v_med3_i32 v127, v127, 32, v206
	v_add_u32_e32 v170, 0xffffff80, v138
	v_add_u32_e32 v138, 0x50, v180
	v_lshl_add_u32 v127, v127, 2, s33
	v_lshl_add_u32 v167, v140, 2, s33
	v_med3_i32 v140, v138, 0, v205
	v_med3_i32 v138, v138, 32, v206
	v_lshl_add_u32 v131, v131, 2, s33
	v_add_u32_e32 v127, 0xffffff80, v127
	v_lshl_add_u32 v139, v139, 2, s33
	v_lshl_add_u32 v171, v140, 2, s33
	v_lshl_add_u32 v138, v138, 2, s33
	v_add_u32_e32 v176, 0xffffff80, v138
	ds_read_b32 v138, v131
	ds_read_b32 v140, v127
	ds_read_b32 v139, v139
	ds_read_b32 v141, v141
	ds_read_b32 v182, v167
	ds_read_b32 v184, v170
	ds_read_b32 v183, v171
	ds_read_b32 v185, v176
	v_add_u32_e32 v127, 0x4b, v180
	v_add_u32_e32 v167, 0x4a, v180
	v_add_u32_e32 v171, 0x49, v180
	v_add_u32_e32 v177, 0x48, v180
	v_med3_i32 v131, v127, 0, v205
	v_med3_i32 v127, v127, 32, v206
	v_med3_i32 v170, v167, 0, v205
	v_med3_i32 v167, v167, 32, v206
	v_med3_i32 v176, v171, 0, v205
	v_med3_i32 v171, v171, 32, v206
	v_med3_i32 v186, v177, 0, v205
	v_med3_i32 v177, v177, 32, v206
	v_lshl_add_u32 v127, v127, 2, s33
	v_lshl_add_u32 v167, v167, 2, s33
	v_lshl_add_u32 v171, v171, 2, s33
	v_lshl_add_u32 v177, v177, 2, s33
	v_lshl_add_u32 v131, v131, 2, s33
	v_add_u32_e32 v127, 0xffffff80, v127
	v_add_u32_e32 v167, 0xffffff80, v167
	v_add_u32_e32 v171, 0xffffff80, v171
	v_lshl_add_u32 v191, v186, 2, s33
	v_add_u32_e32 v177, 0xffffff80, v177
	v_lshl_add_u32 v170, v170, 2, s33
	v_lshl_add_u32 v176, v176, 2, s33
	ds_read_b32 v186, v131
	ds_read_b32 v188, v127
	ds_read_b32 v187, v170
	ds_read_b32 v189, v167
	ds_read_b32 v190, v176
	ds_read_b32 v192, v171
	ds_read_b32 v191, v191
	ds_read_b32 v193, v177
	v_add_u32_e32 v127, 0x43, v180
	v_add_u32_e32 v167, 0x42, v180
	v_add_u32_e32 v171, 0x41, v180
	v_add_u32_e32 v177, 64, v180
	v_med3_i32 v131, v127, 0, v205
	v_med3_i32 v127, v127, 32, v206
	v_med3_i32 v170, v167, 0, v205
	v_med3_i32 v167, v167, 32, v206
	v_med3_i32 v176, v171, 0, v205
	v_med3_i32 v171, v171, 32, v206
	v_med3_i32 v194, v177, 0, v205
	v_med3_i32 v177, v177, 32, v206
	v_lshl_add_u32 v131, v131, 2, s33
	v_lshl_add_u32 v127, v127, 2, s33
	v_lshl_add_u32 v167, v167, 2, s33
	v_lshl_add_u32 v171, v171, 2, s33
	v_lshl_add_u32 v195, v194, 2, s33
	v_lshl_add_u32 v177, v177, 2, s33
	v_add_u32_e32 v127, 0xffffff80, v127
	v_lshl_add_u32 v170, v170, 2, s33
	v_add_u32_e32 v167, 0xffffff80, v167
	v_lshl_add_u32 v176, v176, 2, s33
	v_add_u32_e32 v171, 0xffffff80, v171
	v_add_u32_e32 v177, 0xffffff80, v177
	ds_read_b32 v194, v131
	ds_read_b32 v196, v127
	ds_read_b32 v208, v176
	ds_read_b32 v209, v195
	ds_read_b32 v195, v170
	ds_read_b32 v211, v177
	ds_read_b32 v210, v171
	ds_read_b32 v197, v167
	s_waitcnt lgkmcnt(4)
	v_pk_add_f32 v[96:97], v[96:97], v[208:209]
	s_waitcnt lgkmcnt(3)
	v_pk_add_f32 v[94:95], v[94:95], v[194:195]
	v_pk_add_f32 v[92:93], v[92:93], v[190:191]
	v_pk_add_f32 v[90:91], v[90:91], v[186:187]
	v_pk_add_f32 v[88:89], v[88:89], v[182:183]
	v_pk_add_f32 v[86:87], v[86:87], v[138:139]
	v_pk_add_f32 v[84:85], v[84:85], v[134:135]
	v_pk_add_f32 v[82:83], v[82:83], v[128:129]
	s_waitcnt lgkmcnt(1)
	v_pk_add_f32 v[80:81], v[80:81], v[210:211]
	s_waitcnt lgkmcnt(0)
	v_pk_add_f32 v[78:79], v[78:79], v[196:197]
	v_pk_add_f32 v[76:77], v[76:77], v[192:193]
	v_pk_add_f32 v[74:75], v[74:75], v[188:189]
	v_pk_add_f32 v[72:73], v[72:73], v[184:185]
	v_pk_add_f32 v[70:71], v[70:71], v[140:141]
	v_pk_add_f32 v[68:69], v[68:69], v[136:137]
	v_pk_add_f32 v[66:67], v[66:67], v[132:133]

; template <int VB>
; __device__ __forceinline__ void pv_tile(f32x16* o, int vb0, bf16x8 pa0, bf16x8 pa1, bf16x8 pa2, bf16x8 pa3) {
;     ...
;     PV_D0(0); PV_D0(1); PV_D0(2); PV_D0(3);
.LBB0_703:
	ds_read_b64_tr_b16 v[146:147], v153 offset:0x4000
	ds_read_b64_tr_b16 v[148:149], v153 offset:0x4800
	ds_read_b64_tr_b16 v[186:187], v153 offset:0x5000
	ds_read_b64_tr_b16 v[188:189], v153 offset:0x5800
	ds_read_b64_tr_b16 v[190:191], v153 offset:0x6000
	ds_read_b64_tr_b16 v[192:193], v153 offset:0x6800
	ds_read_b64_tr_b16 v[194:195], v153 offset:0x7000
	ds_read_b64_tr_b16 v[196:197], v153 offset:0x7800
	s_waitcnt lgkmcnt(6)
	s_nop 0
	v_mfma_f32_32x32x16_bf16 v[50:65], v[126:129], v[146:149], v[50:65]
	ds_read_b64_tr_b16 v[146:147], v153 offset:0x4200
	ds_read_b64_tr_b16 v[148:149], v153 offset:0x4a00
	s_waitcnt lgkmcnt(6)
	v_mfma_f32_32x32x16_bf16 v[50:65], v[130:133], v[186:189], v[50:65]
	ds_read_b64_tr_b16 v[186:187], v153 offset:0x5200
	ds_read_b64_tr_b16 v[188:189], v153 offset:0x5a00
	s_waitcnt lgkmcnt(6)
	v_mfma_f32_32x32x16_bf16 v[50:65], v[138:141], v[190:193], v[50:65]
	ds_read_b64_tr_b16 v[190:191], v153 offset:0x6200
	ds_read_b64_tr_b16 v[192:193], v153 offset:0x6a00
	s_waitcnt lgkmcnt(6)
	v_mfma_f32_32x32x16_bf16 v[50:65], v[134:137], v[194:197], v[50:65]
	ds_read_b64_tr_b16 v[194:195], v153 offset:0x7200
	ds_read_b64_tr_b16 v[196:197], v153 offset:0x7a00
	s_waitcnt lgkmcnt(0)
	v_mfma_f32_32x32x16_bf16 v[34:49], v[126:129], v[146:149], v[34:49]
	ds_read_b64_tr_b16 v[146:147], v153 offset:0x4400
	ds_read_b64_tr_b16 v[148:149], v153 offset:0x4c00
	v_mfma_f32_32x32x16_bf16 v[34:49], v[130:133], v[186:189], v[34:49]
	ds_read_b64_tr_b16 v[186:187], v153 offset:0x5400
	ds_read_b64_tr_b16 v[188:189], v153 offset:0x5c00
	v_mfma_f32_32x32x16_bf16 v[34:49], v[138:141], v[190:193], v[34:49]
	ds_read_b64_tr_b16 v[190:191], v153 offset:0x6400
	ds_read_b64_tr_b16 v[192:193], v153 offset:0x6c00
	v_mfma_f32_32x32x16_bf16 v[34:49], v[134:137], v[194:197], v[34:49]
	ds_read_b64_tr_b16 v[194:195], v153 offset:0x7400
	ds_read_b64_tr_b16 v[196:197], v153 offset:0x7c00
	s_waitcnt lgkmcnt(0)
	v_mfma_f32_32x32x16_bf16 v[18:33], v[126:129], v[146:149], v[18:33]
	ds_read_b64_tr_b16 v[146:147], v153 offset:0x4600
	ds_read_b64_tr_b16 v[148:149], v153 offset:0x4e00
	v_mfma_f32_32x32x16_bf16 v[18:33], v[130:133], v[186:189], v[18:33]
	ds_read_b64_tr_b16 v[186:187], v153 offset:0x5600
	ds_read_b64_tr_b16 v[188:189], v153 offset:0x5e00
	v_mfma_f32_32x32x16_bf16 v[18:33], v[138:141], v[190:193], v[18:33]
	ds_read_b64_tr_b16 v[190:191], v153 offset:0x6600
	ds_read_b64_tr_b16 v[192:193], v153 offset:0x6e00
	v_mfma_f32_32x32x16_bf16 v[18:33], v[134:137], v[194:197], v[18:33]
	ds_read_b64_tr_b16 v[194:195], v153 offset:0x7600
	ds_read_b64_tr_b16 v[196:197], v153 offset:0x7e00
	s_waitcnt lgkmcnt(0)
	v_mfma_f32_32x32x16_bf16 v[2:17], v[126:129], v[146:149], v[2:17]
	s_add_i32 s4, s21, 0x71
	s_cmp_le_i32 s4, s30
	v_add_u32_e32 v126, 27, v180
	v_mfma_f32_32x32x16_bf16 v[2:17], v[130:133], v[186:189], v[2:17]
	v_mfma_f32_32x32x16_bf16 v[2:17], v[138:141], v[190:193], v[2:17]
	v_mfma_f32_32x32x16_bf16 v[2:17], v[134:137], v[194:197], v[2:17]
	s_cbranch_scc1 .LBB0_705
; __device__ __forceinline__ void bias_tile(f32x16& p0, f32x16& p1, int dq, const float* tb) {
; #pragma unroll
;     for (int r = 0; r < 16; ++r) {
;         const int c = (r & 3) + 8 * (r >> 2);
;         int d0 = dq - c, d1 = dq - c - 32;
;         d0 = d0 < 0 ? 0 : (d0 > 127 ? 127 : d0); d1 = d1 < 0 ? 0 : (d1 > 127 ? 127 : d1);
;         p0[r] += tb[d0]; p1[r] += tb[d1];
;     }
; }
	v_med3_i32 v128, v126, 32, v206
	v_lshl_add_u32 v128, v128, 2, s33
	v_add_u32_e32 v129, 0xffffff80, v128
	v_add_u32_e32 v128, 26, v180
	v_med3_i32 v130, v128, 0, v205
	v_med3_i32 v128, v128, 32, v206
	v_lshl_add_u32 v128, v128, 2, s33
	v_add_u32_e32 v132, 0xffffff80, v128
	v_add_u32_e32 v128, 25, v180
	v_lshl_add_u32 v131, v130, 2, s33
	v_med3_i32 v130, v128, 0, v205
	v_med3_i32 v128, v128, 32, v206
	v_add_u32_e32 v137, 18, v180
	v_lshl_add_u32 v128, v128, 2, s33
	v_med3_i32 v138, v137, 0, v205
	v_med3_i32 v137, v137, 32, v206
	v_add_u32_e32 v134, 0xffffff80, v128
	v_add_u32_e32 v128, 24, v180
	v_lshl_add_u32 v137, v137, 2, s33
	v_med3_i32 v127, v126, 0, v205
	v_lshl_add_u32 v133, v130, 2, s33
	v_med3_i32 v130, v128, 0, v205
	v_med3_i32 v128, v128, 32, v206
	v_add_u32_e32 v140, 0xffffff80, v137
	v_add_u32_e32 v137, 17, v180
	v_add_u32_e32 v149, 10, v180
	v_lshl_add_u32 v127, v127, 2, s33
	v_lshl_add_u32 v135, v130, 2, s33
	v_lshl_add_u32 v128, v128, 2, s33
	v_lshl_add_u32 v139, v138, 2, s33
	v_med3_i32 v138, v137, 0, v205
	v_med3_i32 v137, v137, 32, v206
	v_med3_i32 v167, v149, 0, v205
	v_med3_i32 v149, v149, 32, v206
	v_add_u32_e32 v136, 0xffffff80, v128
	ds_read_b32 v128, v127
	ds_read_b32 v130, v129
	ds_read_b32 v129, v131
	ds_read_b32 v131, v132
	ds_read_b32 v132, v133
	ds_read_b32 v134, v134
	ds_read_b32 v133, v135
	ds_read_b32 v135, v136
	v_add_u32_e32 v127, 19, v180
	v_lshl_add_u32 v137, v137, 2, s33
	v_lshl_add_u32 v149, v149, 2, s33
	v_med3_i32 v136, v127, 0, v205
	v_med3_i32 v127, v127, 32, v206
	v_add_u32_e32 v146, 0xffffff80, v137
	v_add_u32_e32 v137, 16, v180
	v_add_u32_e32 v170, 0xffffff80, v149
	v_add_u32_e32 v149, 9, v180
	v_lshl_add_u32 v127, v127, 2, s33
	v_lshl_add_u32 v141, v138, 2, s33
	v_med3_i32 v138, v137, 0, v205
	v_med3_i32 v137, v137, 32, v206
	v_med3_i32 v171, v149, 0, v205
	v_med3_i32 v149, v149, 32, v206
	v_lshl_add_u32 v136, v136, 2, s33
	v_add_u32_e32 v127, 0xffffff80, v127
	v_lshl_add_u32 v147, v138, 2, s33
	v_lshl_add_u32 v137, v137, 2, s33
	v_lshl_add_u32 v149, v149, 2, s33
	v_add_u32_e32 v148, 0xffffff80, v137
	ds_read_b32 v136, v136
	ds_read_b32 v138, v127
	ds_read_b32 v137, v139
	ds_read_b32 v139, v140
	ds_read_b32 v140, v141
	ds_read_b32 v146, v146
	ds_read_b32 v141, v147
	ds_read_b32 v147, v148
	v_add_u32_e32 v127, 11, v180
	v_add_u32_e32 v176, 0xffffff80, v149
	v_add_u32_e32 v149, 8, v180
	v_med3_i32 v148, v127, 0, v205
	v_med3_i32 v127, v127, 32, v206
	v_med3_i32 v177, v149, 0, v205
	v_med3_i32 v149, v149, 32, v206
	v_lshl_add_u32 v127, v127, 2, s33
	v_lshl_add_u32 v149, v149, 2, s33
	v_lshl_add_u32 v148, v148, 2, s33
	v_add_u32_e32 v127, 0xffffff80, v127
	v_add_u32_e32 v191, 0xffffff80, v149
	v_lshl_add_u32 v167, v167, 2, s33
	v_lshl_add_u32 v171, v171, 2, s33
	v_lshl_add_u32 v177, v177, 2, s33
	ds_read_b32 v148, v148
	ds_read_b32 v186, v127
	ds_read_b32 v149, v167
	ds_read_b32 v187, v170
	ds_read_b32 v188, v171
	ds_read_b32 v190, v176
	ds_read_b32 v189, v177
	ds_read_b32 v191, v191
	v_add_u32_e32 v127, 3, v180
	v_add_u32_e32 v170, 2, v180
	v_add_u32_e32 v176, 1, v180
	v_med3_i32 v167, v127, 0, v205
	v_med3_i32 v127, v127, 32, v206
	v_med3_i32 v171, v170, 0, v205
	v_med3_i32 v170, v170, 32, v206
	v_med3_i32 v177, v176, 0, v205
	v_med3_i32 v176, v176, 32, v206
	v_med3_i32 v192, v180, 0, v205
	v_med3_i32 v193, v180, 32, v206
	v_lshl_add_u32 v167, v167, 2, s33
	v_lshl_add_u32 v127, v127, 2, s33
	v_lshl_add_u32 v170, v170, 2, s33
	v_lshl_add_u32 v176, v176, 2, s33
	v_lshl_add_u32 v195, v192, 2, s33
	v_lshl_add_u32 v192, v193, 2, s33
	v_add_u32_e32 v127, 0xffffff80, v127
	v_lshl_add_u32 v171, v171, 2, s33
	v_add_u32_e32 v170, 0xffffff80, v170
	v_lshl_add_u32 v177, v177, 2, s33
	v_add_u32_e32 v176, 0xffffff80, v176
	v_add_u32_e32 v202, 0xffffff80, v192
	ds_read_b32 v192, v167
	ds_read_b32 v194, v127
	ds_read_b32 v196, v177
	ds_read_b32 v197, v195
	ds_read_b32 v193, v171
	ds_read_b32 v209, v202
	ds_read_b32 v208, v176
	ds_read_b32 v195, v170
	s_waitcnt lgkmcnt(4)
	v_pk_add_f32 v[96:97], v[96:97], v[196:197]
	s_waitcnt lgkmcnt(3)
	v_pk_add_f32 v[94:95], v[94:95], v[192:193]
	v_pk_add_f32 v[92:93], v[92:93], v[188:189]
	v_pk_add_f32 v[90:91], v[90:91], v[148:149]
	v_pk_add_f32 v[88:89], v[88:89], v[140:141]
	v_pk_add_f32 v[86:87], v[86:87], v[136:137]
	v_pk_add_f32 v[84:85], v[84:85], v[132:133]
	v_pk_add_f32 v[82:83], v[82:83], v[128:129]
	s_waitcnt lgkmcnt(1)
	v_pk_add_f32 v[80:81], v[80:81], v[208:209]
	s_waitcnt lgkmcnt(0)
	v_pk_add_f32 v[78:79], v[78:79], v[194:195]
	v_pk_add_f32 v[76:77], v[76:77], v[190:191]
	v_pk_add_f32 v[74:75], v[74:75], v[186:187]
	v_pk_add_f32 v[72:73], v[72:73], v[146:147]
	v_pk_add_f32 v[70:71], v[70:71], v[138:139]
	v_pk_add_f32 v[68:69], v[68:69], v[134:135]
	v_pk_add_f32 v[66:67], v[66:67], v[130:131]

; __device__ __forceinline__ void finishSM(f32x16& p0, f32x16& p1, float alpha, float& l_reg, bf16x8& pa0, bf16x8& pa1, bf16x8& pa2, bf16x8& pa3) {
; #pragma unroll
;     for (int r = 0; r < 16; ++r) p1[r] = __builtin_amdgcn_exp2f(p1[r]);
;     float ps = 0;
; #pragma unroll
;     for (int r = 0; r < 16; ++r) ps += p0[r];
; #pragma unroll
;     for (int r = 0; r < 16; ++r) ps += p1[r];
;     { auto rr = __builtin_amdgcn_permlane32_swap(__float_as_uint(ps), __float_as_uint(ps), false, false);
;       ps = __uint_as_float(rr[0]) + __uint_as_float(rr[1]); }
;     l_reg = l_reg * alpha + ps;
;     ...
;     PK4(p0, 0, pa0); PK4(p0, 8, pa1); PK4(p1, 0, pa2); PK4(p1, 8, pa3);
; template <int KB, int DQK>
; __device__ __forceinline__ void qkt(f32x16& p0, f32x16& p1, const char* K_lds, int r32, int hi, const bf16x8* qr, const char* qrl) {
;     constexpr int SHMK = 64 * DQK * 2, NF = DQK / 16, NFR = NF > 8 ? 8 : NF;
;     p0 = f32x16{}; p1 = f32x16{};
;     const char* kb[4];
; #pragma unroll
;     for (int dd = 0; dd < 4; ++dd) kb[dd] = K_lds + KB * SHMK + kswz<DQK>(r32, (dd * 16 + hi * 8) * 2);
; #pragma unroll
;     for (int d0 = 0; d0 < NF; ++d0) { const char* a = kb[d0 & 3] + (d0 >> 2) * 128;
;         bf16x8 b0 = *reinterpret_cast<const bf16x8*>(a);
;         bf16x8 b1 = *reinterpret_cast<const bf16x8*>(a + 32 * DQK * 2);
;         bf16x8 q; if (d0 < NFR) q = qr[d0]; else q = *reinterpret_cast<const bf16x8*>(qrl + (d0 - NFR) * 1024);
;         p0 = __builtin_amdgcn_mfma_f32_32x32x16_bf16(b0, q, p0, 0, 0, 0);
;         p1 = __builtin_amdgcn_mfma_f32_32x32x16_bf16(b1, q, p1, 0, 0, 0); }
.LBB0_715:
	ds_read_b128 v[66:69], v161 offset:40960
	ds_read_b128 v[70:73], v161 offset:45056
	s_waitcnt lgkmcnt(1)
	v_mfma_f32_32x32x16_bf16 v[82:97], v[66:69], v[110:113], 0
	s_waitcnt lgkmcnt(0)
	v_mfma_f32_32x32x16_bf16 v[66:81], v[70:73], v[110:113], 0
	ds_read_b128 v[110:113], v162 offset:40960
	ds_read_b128 v[142:145], v162 offset:45056
	s_waitcnt lgkmcnt(1)
	v_mfma_f32_32x32x16_bf16 v[82:97], v[110:113], v[106:109], v[82:97]
	s_waitcnt lgkmcnt(0)
	v_mfma_f32_32x32x16_bf16 v[66:81], v[142:145], v[106:109], v[66:81]
	ds_read_b128 v[106:109], v163 offset:40960
	ds_read_b128 v[110:113], v163 offset:45056
	s_waitcnt lgkmcnt(1)
	v_mfma_f32_32x32x16_bf16 v[82:97], v[106:109], v[102:105], v[82:97]
	s_waitcnt lgkmcnt(0)
	v_mfma_f32_32x32x16_bf16 v[66:81], v[110:113], v[102:105], v[66:81]
	ds_read_b128 v[102:105], v164 offset:40960
	ds_read_b128 v[106:109], v164 offset:45056
	s_waitcnt lgkmcnt(1)
	v_mfma_f32_32x32x16_bf16 v[82:97], v[102:105], v[98:101], v[82:97]
	s_waitcnt lgkmcnt(0)
	v_mfma_f32_32x32x16_bf16 v[66:81], v[106:109], v[98:101], v[66:81]
	v_add_f32_e32 v0, 0, v149
	v_add_f32_e32 v0, v186, v0
	v_add_f32_e32 v0, v147, v0
	v_add_f32_e32 v0, v183, v0
	v_add_f32_e32 v0, v141, v0
	v_add_f32_e32 v0, v148, v0
	v_add_f32_e32 v0, v140, v0
	v_add_f32_e32 v0, v146, v0
	v_add_f32_e32 v0, v137, v0
	v_add_f32_e32 v0, v139, v0
	v_add_f32_e32 v0, v135, v0
	v_add_f32_e32 v0, v138, v0
	v_exp_f32_e32 v99, v122
	v_add_f32_e32 v0, v133, v0
	v_exp_f32_e32 v108, v123
	v_add_f32_e32 v0, v136, v0
	v_exp_f32_e32 v109, v126
	v_add_f32_e32 v0, v132, v0
	v_exp_f32_e32 v110, v127
	v_add_f32_e32 v0, v134, v0
	v_exp_f32_e32 v111, v114
	v_add_f32_e32 v0, v99, v0
	v_exp_f32_e32 v112, v115
	v_add_f32_e32 v0, v108, v0
	v_exp_f32_e32 v113, v120
	v_add_f32_e32 v0, v109, v0
	v_exp_f32_e32 v114, v121
	v_add_f32_e32 v0, v110, v0
	v_exp_f32_e32 v115, v124
	v_add_f32_e32 v0, v111, v0
	v_exp_f32_e32 v120, v125
	v_add_f32_e32 v0, v112, v0
	v_exp_f32_e32 v121, v128
	v_add_f32_e32 v0, v113, v0
	v_exp_f32_e32 v122, v129
	v_add_f32_e32 v0, v114, v0
	v_exp_f32_e32 v116, v116
	v_add_f32_e32 v0, v115, v0
	v_exp_f32_e32 v117, v117
	v_add_f32_e32 v0, v120, v0
	v_exp_f32_e32 v118, v118
	v_add_f32_e32 v0, v121, v0
	v_exp_f32_e32 v119, v119
	v_add_f32_e32 v0, v122, v0
	v_add_f32_e32 v0, v116, v0
	v_add_f32_e32 v0, v117, v0
	v_add_f32_e32 v0, v118, v0
	v_add_f32_e32 v0, v119, v0
	v_mov_b32_e32 v98, v0
	s_nop 1
	v_permlane32_swap_b32_e32 v0, v98
	v_cvt_pk_bf16_f32 v100, v149, v186
	v_cvt_pk_bf16_f32 v101, v147, v183
	v_cvt_pk_bf16_f32 v102, v141, v148
	v_cvt_pk_bf16_f32 v103, v140, v146
	v_cvt_pk_bf16_f32 v104, v137, v139
	v_cvt_pk_bf16_f32 v105, v135, v138
	v_cvt_pk_bf16_f32 v106, v133, v136
	v_cvt_pk_bf16_f32 v107, v132, v134
	v_cvt_pk_bf16_f32 v108, v99, v108
	v_cvt_pk_bf16_f32 v109, v109, v110
	v_cvt_pk_bf16_f32 v110, v111, v112
	v_cvt_pk_bf16_f32 v111, v113, v114
	v_cvt_pk_bf16_f32 v112, v115, v120
	v_cvt_pk_bf16_f32 v113, v121, v122
	v_cvt_pk_bf16_f32 v114, v116, v117
	v_cvt_pk_bf16_f32 v115, v118, v119
	s_nop 0
	v_permlane32_swap_b32_e32 v100, v102
	v_permlane32_swap_b32_e32 v101, v103
	v_permlane32_swap_b32_e32 v104, v106
	v_permlane32_swap_b32_e32 v105, v107
	v_permlane32_swap_b32_e32 v108, v110
	v_permlane32_swap_b32_e32 v109, v111
	v_permlane32_swap_b32_e32 v112, v114
	v_permlane32_swap_b32_e32 v113, v115
	ds_read_b64_tr_b16 v[116:117], v153 offset:0
	ds_read_b64_tr_b16 v[118:119], v153 offset:0x800
	ds_read_b64_tr_b16 v[120:121], v153 offset:0x1000
	ds_read_b64_tr_b16 v[122:123], v153 offset:0x1800
	ds_read_b64_tr_b16 v[124:125], v153 offset:0x2000
	ds_read_b64_tr_b16 v[126:127], v153 offset:0x2800
	ds_read_b64_tr_b16 v[132:133], v153 offset:0x3000
	ds_read_b64_tr_b16 v[134:135], v153 offset:0x3800
	s_waitcnt lgkmcnt(6)
	s_nop 0
	v_mfma_f32_32x32x16_bf16 v[50:65], v[100:103], v[116:119], v[50:65]
	ds_read_b64_tr_b16 v[116:117], v153 offset:0x200
	ds_read_b64_tr_b16 v[118:119], v153 offset:0xa00
	s_waitcnt lgkmcnt(6)
	v_mfma_f32_32x32x16_bf16 v[50:65], v[104:107], v[120:123], v[50:65]
	ds_read_b64_tr_b16 v[120:121], v153 offset:0x1200
	ds_read_b64_tr_b16 v[122:123], v153 offset:0x1a00
	s_waitcnt lgkmcnt(6)
	v_mfma_f32_32x32x16_bf16 v[50:65], v[108:111], v[124:127], v[50:65]
	ds_read_b64_tr_b16 v[124:125], v153 offset:0x2200
	ds_read_b64_tr_b16 v[126:127], v153 offset:0x2a00
	s_waitcnt lgkmcnt(6)
	v_mfma_f32_32x32x16_bf16 v[50:65], v[112:115], v[132:135], v[50:65]
	ds_read_b64_tr_b16 v[132:133], v153 offset:0x3200
	ds_read_b64_tr_b16 v[134:135], v153 offset:0x3a00
	s_waitcnt lgkmcnt(0)
	v_mfma_f32_32x32x16_bf16 v[34:49], v[100:103], v[116:119], v[34:49]
	ds_read_b64_tr_b16 v[116:117], v153 offset:0x400
	ds_read_b64_tr_b16 v[118:119], v153 offset:0xc00
	v_mfma_f32_32x32x16_bf16 v[34:49], v[104:107], v[120:123], v[34:49]
	ds_read_b64_tr_b16 v[120:121], v153 offset:0x1400
	ds_read_b64_tr_b16 v[122:123], v153 offset:0x1c00
	v_mfma_f32_32x32x16_bf16 v[34:49], v[108:111], v[124:127], v[34:49]
	ds_read_b64_tr_b16 v[124:125], v153 offset:0x2400
	ds_read_b64_tr_b16 v[126:127], v153 offset:0x2c00
	v_mfma_f32_32x32x16_bf16 v[34:49], v[112:115], v[132:135], v[34:49]
	ds_read_b64_tr_b16 v[132:133], v153 offset:0x3400
	ds_read_b64_tr_b16 v[134:135], v153 offset:0x3c00
	s_waitcnt lgkmcnt(0)
	v_mfma_f32_32x32x16_bf16 v[18:33], v[100:103], v[116:119], v[18:33]
	ds_read_b64_tr_b16 v[116:117], v153 offset:0x600
	ds_read_b64_tr_b16 v[118:119], v153 offset:0xe00
	v_mfma_f32_32x32x16_bf16 v[18:33], v[104:107], v[120:123], v[18:33]
	ds_read_b64_tr_b16 v[120:121], v153 offset:0x1600
	ds_read_b64_tr_b16 v[122:123], v153 offset:0x1e00
	v_mfma_f32_32x32x16_bf16 v[18:33], v[108:111], v[124:127], v[18:33]
	ds_read_b64_tr_b16 v[124:125], v153 offset:0x2600
	ds_read_b64_tr_b16 v[126:127], v153 offset:0x2e00
	v_mfma_f32_32x32x16_bf16 v[18:33], v[112:115], v[132:135], v[18:33]
	ds_read_b64_tr_b16 v[132:133], v153 offset:0x3600
	ds_read_b64_tr_b16 v[134:135], v153 offset:0x3e00
	s_waitcnt lgkmcnt(0)
	v_mfma_f32_32x32x16_bf16 v[2:17], v[100:103], v[116:119], v[2:17]
	s_or_b32 s4, s18, 0xc0
	s_cmpk_lt_i32 s31, 0x170
	v_subrev_u32_e32 v99, s4, v157
	v_mfma_f32_32x32x16_bf16 v[2:17], v[104:107], v[120:123], v[2:17]
	v_mfma_f32_32x32x16_bf16 v[2:17], v[108:111], v[124:127], v[2:17]
	v_mfma_f32_32x32x16_bf16 v[2:17], v[112:115], v[132:135], v[2:17]
	s_cbranch_scc0 .LBB0_717
; __device__ __forceinline__ void bias_tile(f32x16& p0, f32x16& p1, int dq, const float* tb) {
; #pragma unroll
;     for (int r = 0; r < 16; ++r) {
;         const int c = (r & 3) + 8 * (r >> 2);
;         int d0 = dq - c, d1 = dq - c - 32;
;         d0 = d0 < 0 ? 0 : (d0 > 127 ? 127 : d0); d1 = d1 < 0 ? 0 : (d1 > 127 ? 127 : d1);
;         p0[r] += tb[d0]; p1[r] += tb[d1];
;     }
; }
	v_add_u32_e32 v102, -1, v99
	v_med3_i32 v103, v102, 0, v205
	v_med3_i32 v102, v102, 32, v206
	v_lshl_add_u32 v102, v102, 2, s33
	v_add_u32_e32 v104, 0xffffff80, v102
	v_add_u32_e32 v102, -2, v99
	v_med3_i32 v105, v102, 0, v205
	v_med3_i32 v102, v102, 32, v206
	v_lshl_add_u32 v102, v102, 2, s33
	v_add_u32_e32 v106, 0xffffff80, v102
	v_add_u32_e32 v102, -3, v99
	v_med3_i32 v101, v99, 32, v206
	v_med3_i32 v107, v102, 0, v205
	v_med3_i32 v102, v102, 32, v206
	v_med3_i32 v100, v99, 0, v205
	v_lshl_add_u32 v101, v101, 2, s33
	v_lshl_add_u32 v102, v102, 2, s33
	v_lshl_add_u32 v100, v100, 2, s33
	v_add_u32_e32 v101, 0xffffff80, v101
	v_lshl_add_u32 v103, v103, 2, s33
	v_lshl_add_u32 v105, v105, 2, s33
	v_lshl_add_u32 v107, v107, 2, s33
	v_add_u32_e32 v108, 0xffffff80, v102
	ds_read_b32 v100, v100
	ds_read_b32 v102, v101
	ds_read_b32 v101, v103
	ds_read_b32 v103, v104
	ds_read_b32 v104, v105
	ds_read_b32 v106, v106
	ds_read_b32 v105, v107
	ds_read_b32 v107, v108
	v_add_u32_e32 v108, -8, v99
	v_med3_i32 v109, v108, 0, v205
	v_med3_i32 v108, v108, 32, v206
	v_lshl_add_u32 v108, v108, 2, s33
	v_add_u32_e32 v110, 0xffffff80, v108
	v_add_u32_e32 v108, -9, v99
	v_med3_i32 v111, v108, 0, v205
	v_med3_i32 v108, v108, 32, v206
	v_lshl_add_u32 v108, v108, 2, s33
	v_add_u32_e32 v112, 0xffffff80, v108
	v_add_u32_e32 v108, -10, v99
	v_med3_i32 v113, v108, 0, v205
	v_med3_i32 v108, v108, 32, v206
	v_lshl_add_u32 v108, v108, 2, s33
	v_add_u32_e32 v114, 0xffffff80, v108
	v_add_u32_e32 v108, -11, v99
	v_med3_i32 v115, v108, 0, v205
	v_med3_i32 v108, v108, 32, v206
	v_lshl_add_u32 v108, v108, 2, s33
	v_lshl_add_u32 v109, v109, 2, s33
	v_lshl_add_u32 v111, v111, 2, s33
	v_lshl_add_u32 v113, v113, 2, s33
	v_lshl_add_u32 v115, v115, 2, s33
	v_add_u32_e32 v116, 0xffffff80, v108
	ds_read_b32 v108, v109
	ds_read_b32 v110, v110
	ds_read_b32 v109, v111
	ds_read_b32 v111, v112
	ds_read_b32 v112, v113
	ds_read_b32 v114, v114
	ds_read_b32 v113, v115
	ds_read_b32 v115, v116
	v_add_u32_e32 v116, -16, v99
	v_med3_i32 v117, v116, 0, v205
	v_med3_i32 v116, v116, 32, v206
	v_lshl_add_u32 v116, v116, 2, s33
	v_add_u32_e32 v118, 0xffffff80, v116
	v_subrev_u32_e32 v116, 17, v99
	v_med3_i32 v119, v116, 0, v205
	v_med3_i32 v116, v116, 32, v206
	v_lshl_add_u32 v116, v116, 2, s33
	v_add_u32_e32 v120, 0xffffff80, v116
	v_subrev_u32_e32 v116, 18, v99
	v_med3_i32 v121, v116, 0, v205
	v_med3_i32 v116, v116, 32, v206
	v_lshl_add_u32 v116, v116, 2, s33
	v_add_u32_e32 v122, 0xffffff80, v116
	v_subrev_u32_e32 v116, 19, v99
	v_med3_i32 v123, v116, 0, v205
	v_med3_i32 v116, v116, 32, v206
	v_lshl_add_u32 v116, v116, 2, s33
	v_lshl_add_u32 v117, v117, 2, s33
	v_lshl_add_u32 v119, v119, 2, s33
	v_lshl_add_u32 v121, v121, 2, s33
	v_lshl_add_u32 v123, v123, 2, s33
	v_add_u32_e32 v124, 0xffffff80, v116
	ds_read_b32 v116, v117
	ds_read_b32 v118, v118
	ds_read_b32 v117, v119
	ds_read_b32 v119, v120
	ds_read_b32 v120, v121
	ds_read_b32 v122, v122
	ds_read_b32 v121, v123
	ds_read_b32 v123, v124
	v_subrev_u32_e32 v124, 24, v99
	v_med3_i32 v125, v124, 0, v205
	v_med3_i32 v124, v124, 32, v206
	v_lshl_add_u32 v124, v124, 2, s33
	v_add_u32_e32 v126, 0xffffff80, v124
	v_subrev_u32_e32 v124, 25, v99
	v_med3_i32 v127, v124, 0, v205
	v_med3_i32 v124, v124, 32, v206
	v_lshl_add_u32 v124, v124, 2, s33
	v_add_u32_e32 v134, 0xffffff80, v124
	v_subrev_u32_e32 v124, 26, v99
	v_med3_i32 v128, v124, 0, v205
	v_med3_i32 v124, v124, 32, v206
	v_lshl_add_u32 v124, v124, 2, s33
	v_add_u32_e32 v132, 0xffffff80, v124
	v_subrev_u32_e32 v124, 27, v99
	v_med3_i32 v129, v124, 0, v205
	v_med3_i32 v124, v124, 32, v206
	v_lshl_add_u32 v124, v124, 2, s33
	v_lshl_add_u32 v125, v125, 2, s33
	v_lshl_add_u32 v127, v127, 2, s33
	v_lshl_add_u32 v128, v128, 2, s33
	v_lshl_add_u32 v129, v129, 2, s33
	v_add_u32_e32 v133, 0xffffff80, v124
	ds_read_b32 v124, v125
	ds_read_b32 v126, v126
	ds_read_b32 v128, v128
	ds_read_b32 v129, v129
	ds_read_b32 v125, v127
	ds_read_b32 v133, v133
	ds_read_b32 v132, v132
	ds_read_b32 v127, v134
	s_waitcnt lgkmcnt(4)
	v_pk_add_f32 v[96:97], v[96:97], v[128:129]
	s_waitcnt lgkmcnt(3)
	v_pk_add_f32 v[94:95], v[94:95], v[124:125]
	v_pk_add_f32 v[92:93], v[92:93], v[120:121]
	v_pk_add_f32 v[90:91], v[90:91], v[116:117]
	v_pk_add_f32 v[88:89], v[88:89], v[112:113]
	v_pk_add_f32 v[86:87], v[86:87], v[108:109]
	v_pk_add_f32 v[84:85], v[84:85], v[104:105]
	v_pk_add_f32 v[82:83], v[82:83], v[100:101]
	s_waitcnt lgkmcnt(1)
	v_pk_add_f32 v[80:81], v[80:81], v[132:133]
	s_waitcnt lgkmcnt(0)
	v_pk_add_f32 v[78:79], v[78:79], v[126:127]
	v_pk_add_f32 v[76:77], v[76:77], v[122:123]
	v_pk_add_f32 v[74:75], v[74:75], v[118:119]
	v_pk_add_f32 v[72:73], v[72:73], v[114:115]
	v_pk_add_f32 v[70:71], v[70:71], v[110:111]
	v_pk_add_f32 v[68:69], v[68:69], v[106:107]
	v_pk_add_f32 v[66:67], v[66:67], v[102:103]

; __device__ __forceinline__ void partialSM(f32x16& p0, f32x16& p1, float& m_reg, float& mn, float& alpha) {
;     ...
;     for (int r = 0; r < 16; ++r) p0[r] = p0[r] - mn;
; #pragma unroll
;     for (int r = 0; r < 16; ++r) p1[r] = p1[r] - mn;
; #pragma unroll
;     for (int r = 0; r < 16; ++r) p0[r] = __builtin_amdgcn_exp2f(p0[r]);
; }
; __device__ __forceinline__ void finishSM(f32x16& p0, f32x16& p1, float alpha, float& l_reg, bf16x8& pa0, bf16x8& pa1, bf16x8& pa2, bf16x8& pa3) {
; #pragma unroll
;     for (int r = 0; r < 16; ++r) p1[r] = __builtin_amdgcn_exp2f(p1[r]);
;     float ps = 0;
; #pragma unroll
;     for (int r = 0; r < 16; ++r) ps += p0[r];
; #pragma unroll
;     for (int r = 0; r < 16; ++r) ps += p1[r];
;     { auto rr = __builtin_amdgcn_permlane32_swap(__float_as_uint(ps), __float_as_uint(ps), false, false);
;       ps = __uint_as_float(rr[0]) + __uint_as_float(rr[1]); }
;     l_reg = l_reg * alpha + ps;
;     ...
;     PK4(p0, 0, pa0); PK4(p0, 8, pa1); PK4(p1, 0, pa2); PK4(p1, 8, pa3);
; template <int VB>
; __device__ __forceinline__ void pv_tile(f32x16* o, int vb0, bf16x8 pa0, bf16x8 pa1, bf16x8 pa2, bf16x8 pa3) {
;     ...
;     PV_D0(0); PV_D0(1); PV_D0(2); PV_D0(3);
.LBB0_723:
	v_cndmask_b32_e64 v100, v100, v130, s[44:45]
	v_sub_f32_e32 v82, v82, v100
	v_sub_f32_e32 v83, v83, v100
	v_exp_f32_e32 v82, v82
	v_sub_f32_e32 v84, v84, v100
	v_exp_f32_e32 v83, v83
	v_sub_f32_e32 v85, v85, v100
	v_exp_f32_e32 v84, v84
	v_sub_f32_e32 v86, v86, v100
	v_sub_f32_e32 v66, v66, v100
	v_exp_f32_e32 v85, v85
	v_sub_f32_e32 v87, v87, v100
	v_sub_f32_e32 v88, v88, v100
	v_sub_f32_e32 v89, v89, v100
	v_sub_f32_e32 v90, v90, v100
	v_sub_f32_e32 v91, v91, v100
	v_sub_f32_e32 v92, v92, v100
	v_sub_f32_e32 v93, v93, v100
	v_sub_f32_e32 v94, v94, v100
	v_sub_f32_e32 v95, v95, v100
	v_sub_f32_e32 v96, v96, v100
	v_sub_f32_e32 v97, v97, v100
	v_sub_f32_e32 v67, v67, v100
	v_sub_f32_e32 v68, v68, v100
	v_sub_f32_e32 v69, v69, v100
	v_sub_f32_e32 v70, v70, v100
	v_sub_f32_e32 v71, v71, v100
	v_sub_f32_e32 v72, v72, v100
	v_sub_f32_e32 v73, v73, v100
	v_sub_f32_e32 v74, v74, v100
	v_sub_f32_e32 v75, v75, v100
	v_sub_f32_e32 v76, v76, v100
	v_sub_f32_e32 v77, v77, v100
	v_sub_f32_e32 v78, v78, v100
	v_sub_f32_e32 v79, v79, v100
	v_sub_f32_e32 v80, v80, v100
	v_sub_f32_e32 v81, v81, v100
	v_exp_f32_e32 v86, v86
	v_exp_f32_e32 v100, v66
	v_add_f32_e32 v66, 0, v82
	v_exp_f32_e32 v87, v87
	v_add_f32_e32 v66, v83, v66
	v_exp_f32_e32 v88, v88
	v_add_f32_e32 v66, v84, v66
	v_exp_f32_e32 v89, v89
	v_add_f32_e32 v66, v85, v66
	v_exp_f32_e32 v90, v90
	v_add_f32_e32 v66, v86, v66
	v_exp_f32_e32 v91, v91
	v_add_f32_e32 v66, v87, v66
	v_exp_f32_e32 v92, v92
	v_add_f32_e32 v66, v88, v66
	v_exp_f32_e32 v93, v93
	v_add_f32_e32 v66, v89, v66
	v_exp_f32_e32 v94, v94
	v_add_f32_e32 v66, v90, v66
	v_exp_f32_e32 v95, v95
	v_add_f32_e32 v66, v91, v66
	v_exp_f32_e32 v96, v96
	v_add_f32_e32 v66, v92, v66
	v_exp_f32_e32 v97, v97
	v_add_f32_e32 v66, v93, v66
	v_add_f32_e32 v66, v94, v66
	v_exp_f32_e32 v101, v67
	v_add_f32_e32 v66, v95, v66
	v_exp_f32_e32 v102, v68
	v_add_f32_e32 v66, v96, v66
	v_exp_f32_e32 v103, v69
	v_add_f32_e32 v66, v97, v66
	v_exp_f32_e32 v104, v70
	v_add_f32_e32 v66, v100, v66
	v_exp_f32_e32 v105, v71
	v_add_f32_e32 v66, v101, v66
	v_exp_f32_e32 v106, v72
	v_add_f32_e32 v66, v102, v66
	v_exp_f32_e32 v107, v73
	v_add_f32_e32 v66, v103, v66
	v_exp_f32_e32 v108, v74
	v_add_f32_e32 v66, v104, v66
	v_exp_f32_e32 v109, v75
	v_add_f32_e32 v66, v105, v66
	v_exp_f32_e32 v110, v76
	v_add_f32_e32 v66, v106, v66
	v_exp_f32_e32 v111, v77
	v_add_f32_e32 v66, v107, v66
	v_exp_f32_e32 v112, v78
	v_add_f32_e32 v66, v108, v66
	v_exp_f32_e32 v113, v79
	v_add_f32_e32 v66, v109, v66
	v_exp_f32_e32 v114, v80
	v_add_f32_e32 v66, v110, v66
	v_exp_f32_e32 v115, v81
	v_add_f32_e32 v66, v111, v66
	v_add_f32_e32 v66, v112, v66
	v_add_f32_e32 v66, v113, v66
	v_add_f32_e32 v66, v114, v66
	v_add_f32_e32 v66, v115, v66
	v_mov_b32_e32 v67, v66
	s_nop 1
	v_permlane32_swap_b32_e32 v66, v67
	v_cvt_pk_bf16_f32 v68, v82, v83
	v_cvt_pk_bf16_f32 v69, v84, v85
	v_cvt_pk_bf16_f32 v70, v86, v87
	v_cvt_pk_bf16_f32 v71, v88, v89
	v_cvt_pk_bf16_f32 v72, v90, v91
	v_cvt_pk_bf16_f32 v73, v92, v93
	v_cvt_pk_bf16_f32 v74, v94, v95
	v_cvt_pk_bf16_f32 v75, v96, v97
	v_cvt_pk_bf16_f32 v76, v100, v101
	v_cvt_pk_bf16_f32 v77, v102, v103
	v_cvt_pk_bf16_f32 v78, v104, v105
	v_cvt_pk_bf16_f32 v79, v106, v107
	v_cvt_pk_bf16_f32 v80, v108, v109
	v_cvt_pk_bf16_f32 v81, v110, v111
	v_cvt_pk_bf16_f32 v82, v112, v113
	v_cvt_pk_bf16_f32 v83, v114, v115
	s_nop 0
	v_permlane32_swap_b32_e32 v68, v70
	v_permlane32_swap_b32_e32 v69, v71
	v_permlane32_swap_b32_e32 v72, v74
	v_permlane32_swap_b32_e32 v73, v75
	v_permlane32_swap_b32_e32 v76, v78
	v_permlane32_swap_b32_e32 v77, v79
	v_permlane32_swap_b32_e32 v80, v82
	v_permlane32_swap_b32_e32 v81, v83
	ds_read_b64_tr_b16 v[84:85], v153 offset:0x4000
	ds_read_b64_tr_b16 v[86:87], v153 offset:0x4800
	ds_read_b64_tr_b16 v[88:89], v153 offset:0x5000
	ds_read_b64_tr_b16 v[90:91], v153 offset:0x5800
	ds_read_b64_tr_b16 v[92:93], v153 offset:0x6000
	ds_read_b64_tr_b16 v[94:95], v153 offset:0x6800
	ds_read_b64_tr_b16 v[100:101], v153 offset:0x7000
	ds_read_b64_tr_b16 v[102:103], v153 offset:0x7800
	s_waitcnt lgkmcnt(6)
	s_nop 0
	v_mfma_f32_32x32x16_bf16 v[50:65], v[68:71], v[84:87], v[50:65]
	ds_read_b64_tr_b16 v[84:85], v153 offset:0x4200
	ds_read_b64_tr_b16 v[86:87], v153 offset:0x4a00
	s_waitcnt lgkmcnt(6)
	v_mfma_f32_32x32x16_bf16 v[50:65], v[72:75], v[88:91], v[50:65]
	ds_read_b64_tr_b16 v[88:89], v153 offset:0x5200
	ds_read_b64_tr_b16 v[90:91], v153 offset:0x5a00
	s_waitcnt lgkmcnt(6)
	v_mfma_f32_32x32x16_bf16 v[50:65], v[76:79], v[92:95], v[50:65]
	ds_read_b64_tr_b16 v[92:93], v153 offset:0x6200
	ds_read_b64_tr_b16 v[94:95], v153 offset:0x6a00
	s_waitcnt lgkmcnt(6)
	v_mfma_f32_32x32x16_bf16 v[50:65], v[80:83], v[100:103], v[50:65]
	ds_read_b64_tr_b16 v[100:101], v153 offset:0x7200
	ds_read_b64_tr_b16 v[102:103], v153 offset:0x7a00
	s_waitcnt lgkmcnt(0)
	v_mfma_f32_32x32x16_bf16 v[34:49], v[68:71], v[84:87], v[34:49]
	ds_read_b64_tr_b16 v[84:85], v153 offset:0x4400
	ds_read_b64_tr_b16 v[86:87], v153 offset:0x4c00
	v_mfma_f32_32x32x16_bf16 v[34:49], v[72:75], v[88:91], v[34:49]
	ds_read_b64_tr_b16 v[88:89], v153 offset:0x5400
	ds_read_b64_tr_b16 v[90:91], v153 offset:0x5c00
	v_mfma_f32_32x32x16_bf16 v[34:49], v[76:79], v[92:95], v[34:49]
	ds_read_b64_tr_b16 v[92:93], v153 offset:0x6400
	ds_read_b64_tr_b16 v[94:95], v153 offset:0x6c00
	v_mfma_f32_32x32x16_bf16 v[34:49], v[80:83], v[100:103], v[34:49]
	ds_read_b64_tr_b16 v[100:101], v153 offset:0x7400
	ds_read_b64_tr_b16 v[102:103], v153 offset:0x7c00
	s_waitcnt lgkmcnt(0)
	v_mfma_f32_32x32x16_bf16 v[18:33], v[68:71], v[84:87], v[18:33]
	ds_read_b64_tr_b16 v[84:85], v153 offset:0x4600
	ds_read_b64_tr_b16 v[86:87], v153 offset:0x4e00
	v_mfma_f32_32x32x16_bf16 v[18:33], v[72:75], v[88:91], v[18:33]
	ds_read_b64_tr_b16 v[88:89], v153 offset:0x5600
	ds_read_b64_tr_b16 v[90:91], v153 offset:0x5e00
	v_mfma_f32_32x32x16_bf16 v[18:33], v[76:79], v[92:95], v[18:33]
	ds_read_b64_tr_b16 v[92:93], v153 offset:0x6600
	ds_read_b64_tr_b16 v[94:95], v153 offset:0x6e00
	v_mfma_f32_32x32x16_bf16 v[18:33], v[80:83], v[100:103], v[18:33]
	ds_read_b64_tr_b16 v[100:101], v153 offset:0x7600
	ds_read_b64_tr_b16 v[102:103], v153 offset:0x7e00
	s_waitcnt lgkmcnt(0)
	v_mfma_f32_32x32x16_bf16 v[2:17], v[68:71], v[84:87], v[2:17]
	v_mfma_f32_32x32x16_bf16 v[2:17], v[72:75], v[88:91], v[2:17]
	v_mfma_f32_32x32x16_bf16 v[2:17], v[76:79], v[92:95], v[2:17]
	v_mfma_f32_32x32x16_bf16 v[2:17], v[80:83], v[100:103], v[2:17]
	s_barrier
; __device__ __forceinline__ float lane_xor1(float v) { return __builtin_bit_cast(float, __builtin_amdgcn_update_dpp(0, __builtin_bit_cast(int, v), 0xB1, 0xF, 0xF, false)); }
; __device__ __forceinline__ int crow(int r, int hi) { return (r & 3) + 8 * (r >> 2) + 4 * hi; }
; __device__ __forceinline__ unsigned cvtpk(float lo, float hi) { unsigned r; asm volatile("v_cvt_pk_bf16_f32 %0, %1, %2" : "=v"(r) : "v"(lo), "v"(hi)); return r; }
; template <bool MLA, int MODE, bool PIPE>
; __device__ __forceinline__ void attn_block(const AttnArgs& a, char* lds) {
;     ...
;     } else if constexpr (MODE == 1) {
;         bf16_t* Ow = (bf16_t*)a.O0 + (size_t)qlo * 512;
; #pragma unroll
;         for (int r = 0; r < 16; ++r) { const int orow = crow(r, hi);
; #pragma unroll
;             for (int d0 = 0; d0 < 4; ++d0) { const float v = o[d0][r] * rli[r]; const float vn = lane_xor1(v);
;                 if ((r32 & 1) == 0) *(unsigned*)(Ow + (size_t)orow * 512 + d0 * 32 + r32) = cvtpk(v, vn); } }
	s_and_saveexec_b64 s[4:5], s[42:43]
	v_add_f32_e32 v0, v0, v98
	v_fmac_f32_e32 v0, v156, v131
	v_add_f32_e32 v66, v66, v67
	v_fmac_f32_e32 v66, v0, v99
	ds_write_b32 v155, v66
	s_or_b64 exec, exec, s[4:5]
	s_add_u32 s4, s14, s24
	s_addc_u32 s5, s15, s25
	s_add_u32 s4, s4, s2
	s_waitcnt lgkmcnt(0)
	s_addc_u32 s5, s5, s3
	s_lshl_b64 s[2:3], s[0:1], 22
	ds_read_b128 v[78:81], v154
	ds_read_b128 v[74:77], v154 offset:32
	s_add_u32 s4, s4, s2
	s_addc_u32 s5, s5, s3
	s_lshl_b32 s6, s29, 1
	s_add_u32 s6, s4, s6
	s_addc_u32 s7, s5, 0
	s_ashr_i32 s31, s30, 31
	s_waitcnt lgkmcnt(1)
	v_rcp_f32_e32 v78, v78
	s_lshl_b64 s[4:5], s[30:31], 10
	ds_read_b128 v[70:73], v154 offset:64
	ds_read_b128 v[66:69], v154 offset:96
	s_add_u32 s4, s6, s4
	v_and_b32_e32 v0, 1, v151
	s_addc_u32 s5, s7, s5
	v_cmp_eq_u32_e64 s[42:43], 0, v0
	v_lshlrev_b32_e32 v0, 1, v152
	v_lshl_add_u64 v[82:83], s[4:5], 0, v[0:1]
	v_lshlrev_b32_e32 v0, 12, v150
	v_lshl_add_u64 v[82:83], v[82:83], 0, v[0:1]
	v_mul_f32_e32 v0, v50, v78
	v_mov_b32_e32 v50, v1
	s_nop 1
	v_mov_b32_dpp v50, v0 quad_perm:[1,0,3,2] row_mask:0xf bank_mask:0xf
	s_and_saveexec_b64 s[4:5], s[42:43]
	s_cbranch_execz .LBB0_727
	v_cvt_pk_bf16_f32 v0, v0, v50
	global_store_dword v[82:83], v0, off
